# f32 divisions in the GLU / conv-silu / SwiGLU epilogues: v_div_scale+fma+v_div_fmas+v_div_fixup sequences replaced by v_rcp_f32 + v_mul_f32 (f32, ~1 ulp; results are rounded to bf16)
# speedup vs baseline: 1.0636x; 1.0088x over previous
; DI unsigned pk2(float a, float b) { fl2_t f = {a, b}; bf2_t r = __builtin_convertvector(f, bf2_t); return __builtin_bit_cast(unsigned, r); }
; DI void phase2(const Params& p, char* lds) {
;     ...
;       const int j = nt - 12, row = tid & 127, hf = tid >> 7;
;       bfr* dst = (bfr*)(ws + WS_Z) + (size_t)(t0h + row) * 512 + j * 64 + hf * 32;
; #pragma unroll
;       for (int q = 0; q < 4; ++q) {
;         float z[8];
; #pragma unroll
;         for (int u = 0; u < 2; ++u) {
;           float4 a = cs4(Cs, row, hf * 32 + q * 8 + u * 4);
;           float4 g = cs4(Cs, row, 64 + hf * 32 + q * 8 + u * 4);
;           z[u * 4 + 0] = a.x / (1.f + __expf(-g.x)); z[u * 4 + 1] = a.y / (1.f + __expf(-g.y));
;           z[u * 4 + 2] = a.z / (1.f + __expf(-g.z)); z[u * 4 + 3] = a.w / (1.f + __expf(-g.w));
;         }
;         u32x4 o; o[0] = pk2(z[0], z[1]); o[1] = pk2(z[2], z[3]); o[2] = pk2(z[4], z[5]); o[3] = pk2(z[6], z[7]);
;         *(u32x4*)(dst + q * 8) = o;
;       }
.LBB0_125:
	s_cmp_gt_u32 s3, 11
	s_cbranch_scc0 .LBB0_127
	v_add_u32_e32 v2, s44, v166
	ds_read_b128 v[20:23], v167 offset:128
	v_ashrrev_i32_e32 v3, 31, v2
	v_lshlrev_b64 v[2:3], 10, v[2:3]
	s_lshl_b32 s8, s40, 7
	v_lshl_add_u64 v[2:3], s[14:15], 0, v[2:3]
	s_addk_i32 s8, 0xfd00
	v_lshl_add_u64 v[2:3], s[8:9], 1, v[2:3]
	v_lshlrev_b32_e32 v150, 1, v156
	v_lshl_add_u64 v[18:19], v[2:3], 0, v[150:151]
	s_waitcnt lgkmcnt(0)
	v_lshlrev_b32_e32 v2, 16, v20
	v_and_b32_e32 v3, 0xffff0000, v20
	v_mul_f32_e32 v2, 0xbfb8aa3b, v2
	v_exp_f32_e32 v28, v2
	v_mul_f32_e32 v2, 0xbfb8aa3b, v3
	v_exp_f32_e32 v29, v2
	ds_read_b128 v[14:17], v167
	ds_read_b128 v[10:13], v167 offset:16
	ds_read_b128 v[24:27], v167 offset:144
	v_lshlrev_b32_e32 v32, 16, v21
	v_and_b32_e32 v21, 0xffff0000, v21
	s_waitcnt lgkmcnt(2)
	v_and_b32_e32 v20, 0xffff0000, v14
	v_pk_add_f32 v[28:29], v[28:29], 1.0 op_sel_hi:[1,0]
	v_lshlrev_b32_e32 v14, 16, v14
	v_mul_f32_e32 v21, 0xbfb8aa3b, v21
	v_exp_f32_e32 v21, v21
	ds_read_b128 v[6:9], v167 offset:32
	ds_read_b128 v[2:5], v167 offset:48
	v_rcp_f32_e32 v30, v29
	s_nop 0
	v_mul_f32_e32 v29, v20, v30
	v_mul_f32_e32 v20, 0xbfb8aa3b, v32
	v_exp_f32_e32 v20, v20
	v_and_b32_e32 v32, 0xffff0000, v15
	v_pk_add_f32 v[20:21], v[20:21], 1.0 op_sel_hi:[1,0]
	v_rcp_f32_e32 v30, v28
	s_nop 0
	v_mul_f32_e32 v28, v14, v30
	v_lshlrev_b32_e32 v30, 16, v15
	v_rcp_f32_e32 v14, v21
	s_nop 0
	v_mul_f32_e32 v32, v32, v14
	v_lshlrev_b32_e32 v14, 16, v22
	v_and_b32_e32 v15, 0xffff0000, v22
	v_mul_f32_e32 v14, 0xbfb8aa3b, v14
	v_mul_f32_e32 v15, 0xbfb8aa3b, v15
	v_exp_f32_e32 v14, v14
	v_exp_f32_e32 v15, v15
	v_rcp_f32_e32 v21, v20
	s_nop 0
	v_mul_f32_e32 v22, v30, v21
	v_and_b32_e32 v20, 0xffff0000, v16
	v_pk_add_f32 v[14:15], v[14:15], 1.0 op_sel_hi:[1,0]
	v_lshlrev_b32_e32 v16, 16, v16
	v_lshlrev_b32_e32 v31, 16, v23
	v_and_b32_e32 v23, 0xffff0000, v23
	v_rcp_f32_e32 v21, v15
	s_nop 0
	v_mul_f32_e32 v30, v20, v21
	v_mul_f32_e32 v20, 0xbfb8aa3b, v31
	v_mul_f32_e32 v21, 0xbfb8aa3b, v23
	v_exp_f32_e32 v20, v20
	v_exp_f32_e32 v21, v21
	v_and_b32_e32 v23, 0xffff0000, v17
	v_pk_add_f32 v[20:21], v[20:21], 1.0 op_sel_hi:[1,0]
	v_rcp_f32_e32 v15, v14
	s_nop 0
	v_mul_f32_e32 v16, v16, v15
	v_lshlrev_b32_e32 v14, 16, v17
	v_rcp_f32_e32 v15, v21
	s_nop 0
	v_mul_f32_e32 v17, v23, v15
	v_cvt_pk_bf16_f32 v16, v16, v30
	v_rcp_f32_e32 v15, v20
	s_nop 0
	v_mul_f32_e32 v23, v14, v15
	s_waitcnt lgkmcnt(2)
	v_lshlrev_b32_e32 v20, 16, v24
	v_and_b32_e32 v21, 0xffff0000, v24
	v_mul_f32_e32 v20, 0xbfb8aa3b, v20
	v_mul_f32_e32 v21, 0xbfb8aa3b, v21
	v_exp_f32_e32 v20, v20
	v_exp_f32_e32 v21, v21
	v_cvt_pk_bf16_f32 v14, v28, v29
	v_cvt_pk_bf16_f32 v15, v22, v32
	v_cvt_pk_bf16_f32 v17, v23, v17
	global_store_dwordx4 v[18:19], v[14:17], off
	v_and_b32_e32 v22, 0xffff0000, v25
	s_nop 0
	v_and_b32_e32 v16, 0xffff0000, v10
	v_pk_add_f32 v[14:15], v[20:21], 1.0 op_sel_hi:[1,0]
	v_lshlrev_b32_e32 v21, 16, v25
	v_lshlrev_b32_e32 v10, 16, v10
	v_rcp_f32_e32 v17, v15
	s_nop 0
	v_mul_f32_e32 v20, v16, v17
	v_mul_f32_e32 v16, 0xbfb8aa3b, v21
	v_mul_f32_e32 v17, 0xbfb8aa3b, v22
	v_exp_f32_e32 v16, v16
	v_exp_f32_e32 v17, v17
	v_and_b32_e32 v21, 0xffff0000, v11
	v_pk_add_f32 v[16:17], v[16:17], 1.0 op_sel_hi:[1,0]
	v_rcp_f32_e32 v15, v14
	s_nop 0
	v_mul_f32_e32 v24, v10, v15
	v_lshlrev_b32_e32 v14, 16, v11
	v_rcp_f32_e32 v10, v17
	s_nop 0
	v_mul_f32_e32 v17, v21, v10
	v_and_b32_e32 v23, 0xffff0000, v27
	v_lshlrev_b32_e32 v10, 16, v26
	v_and_b32_e32 v11, 0xffff0000, v26
	v_mul_f32_e32 v10, 0xbfb8aa3b, v10
	v_mul_f32_e32 v11, 0xbfb8aa3b, v11
	v_exp_f32_e32 v10, v10
	v_exp_f32_e32 v11, v11
	v_rcp_f32_e32 v15, v16
	s_nop 0
	v_mul_f32_e32 v16, v14, v15
	v_and_b32_e32 v14, 0xffff0000, v12
	v_pk_add_f32 v[10:11], v[10:11], 1.0 op_sel_hi:[1,0]
	v_lshlrev_b32_e32 v22, 16, v27
	v_lshlrev_b32_e32 v12, 16, v12
	v_rcp_f32_e32 v15, v11
	s_nop 0
	v_mul_f32_e32 v21, v14, v15
	v_mul_f32_e32 v14, 0xbfb8aa3b, v22
	v_mul_f32_e32 v15, 0xbfb8aa3b, v23
	v_exp_f32_e32 v14, v14
	v_exp_f32_e32 v15, v15
	v_and_b32_e32 v22, 0xffff0000, v13
	v_pk_add_f32 v[14:15], v[14:15], 1.0 op_sel_hi:[1,0]
	v_rcp_f32_e32 v11, v10
	s_nop 0
	v_mul_f32_e32 v26, v12, v11
	v_lshlrev_b32_e32 v10, 16, v13
	v_rcp_f32_e32 v11, v15
	s_nop 0
	v_mul_f32_e32 v27, v22, v11
	v_rcp_f32_e32 v11, v14
	s_nop 0
	v_mul_f32_e32 v28, v10, v11
	ds_read_b128 v[10:13], v167 offset:160
	v_cvt_pk_bf16_f32 v15, v16, v17
	v_cvt_pk_bf16_f32 v14, v24, v20
	v_cvt_pk_bf16_f32 v16, v26, v21
	ds_read_b128 v[20:23], v167 offset:176
	s_waitcnt lgkmcnt(1)
; DI unsigned pk2(float a, float b) { fl2_t f = {a, b}; bf2_t r = __builtin_convertvector(f, bf2_t); return __builtin_bit_cast(unsigned, r); }
; DI void phase2(const Params& p, char* lds) {
;     ...
;       const int j = nt - 12, row = tid & 127, hf = tid >> 7;
;       bfr* dst = (bfr*)(ws + WS_Z) + (size_t)(t0h + row) * 512 + j * 64 + hf * 32;
; #pragma unroll
;       for (int q = 0; q < 4; ++q) {
;         float z[8];
; #pragma unroll
;         for (int u = 0; u < 2; ++u) {
;           float4 a = cs4(Cs, row, hf * 32 + q * 8 + u * 4);
;           float4 g = cs4(Cs, row, 64 + hf * 32 + q * 8 + u * 4);
;           z[u * 4 + 0] = a.x / (1.f + __expf(-g.x)); z[u * 4 + 1] = a.y / (1.f + __expf(-g.y));
;           z[u * 4 + 2] = a.z / (1.f + __expf(-g.z)); z[u * 4 + 3] = a.w / (1.f + __expf(-g.w));
;         }
;         u32x4 o; o[0] = pk2(z[0], z[1]); o[1] = pk2(z[2], z[3]); o[2] = pk2(z[4], z[5]); o[3] = pk2(z[6], z[7]);
;         *(u32x4*)(dst + q * 8) = o;
;       }
	v_lshlrev_b32_e32 v17, 16, v10
	v_and_b32_e32 v10, 0xffff0000, v10
	v_mul_f32_e32 v17, 0xbfb8aa3b, v17
	v_mul_f32_e32 v10, 0xbfb8aa3b, v10
	v_exp_f32_e32 v24, v17
	v_exp_f32_e32 v25, v10
	v_cvt_pk_bf16_f32 v17, v28, v27
	global_store_dwordx4 v[18:19], v[14:17], off offset:16
	v_and_b32_e32 v10, 0xffff0000, v6
	v_lshlrev_b32_e32 v6, 16, v6
	v_pk_add_f32 v[14:15], v[24:25], 1.0 op_sel_hi:[1,0]
	v_lshlrev_b32_e32 v24, 16, v11
	v_and_b32_e32 v11, 0xffff0000, v11
	v_mul_f32_e32 v11, 0xbfb8aa3b, v11
	v_exp_f32_e32 v11, v11
	v_rcp_f32_e32 v16, v15
	s_nop 0
	v_mul_f32_e32 v15, v10, v16
	v_mul_f32_e32 v10, 0xbfb8aa3b, v24
	v_exp_f32_e32 v10, v10
	v_and_b32_e32 v24, 0xffff0000, v7
	v_pk_add_f32 v[10:11], v[10:11], 1.0 op_sel_hi:[1,0]
	v_rcp_f32_e32 v16, v14
	s_nop 0
	v_mul_f32_e32 v14, v6, v16
	v_lshlrev_b32_e32 v16, 16, v7
	v_rcp_f32_e32 v6, v11
	s_nop 0
	v_mul_f32_e32 v24, v24, v6
	v_lshlrev_b32_e32 v6, 16, v12
	v_and_b32_e32 v7, 0xffff0000, v12
	v_mul_f32_e32 v6, 0xbfb8aa3b, v6
	v_mul_f32_e32 v7, 0xbfb8aa3b, v7
	v_exp_f32_e32 v6, v6
	v_exp_f32_e32 v7, v7
	v_rcp_f32_e32 v11, v10
	s_nop 0
	v_mul_f32_e32 v12, v16, v11
	v_and_b32_e32 v10, 0xffff0000, v8
	v_pk_add_f32 v[6:7], v[6:7], 1.0 op_sel_hi:[1,0]
	v_lshlrev_b32_e32 v8, 16, v8
	v_lshlrev_b32_e32 v17, 16, v13
	v_and_b32_e32 v13, 0xffff0000, v13
	v_rcp_f32_e32 v11, v7
	s_nop 0
	v_mul_f32_e32 v16, v10, v11
	v_mul_f32_e32 v10, 0xbfb8aa3b, v17
	v_mul_f32_e32 v11, 0xbfb8aa3b, v13
	v_exp_f32_e32 v10, v10
	v_exp_f32_e32 v11, v11
	v_and_b32_e32 v13, 0xffff0000, v9
	v_pk_add_f32 v[10:11], v[10:11], 1.0 op_sel_hi:[1,0]
	v_rcp_f32_e32 v7, v6
	s_nop 0
	v_mul_f32_e32 v8, v8, v7
	v_lshlrev_b32_e32 v6, 16, v9
	v_rcp_f32_e32 v7, v11
	s_nop 0
	v_mul_f32_e32 v9, v13, v7
	v_cvt_pk_bf16_f32 v8, v8, v16
	v_rcp_f32_e32 v7, v10
	s_nop 0
	v_mul_f32_e32 v13, v6, v7
	s_waitcnt lgkmcnt(0)
	v_lshlrev_b32_e32 v10, 16, v20
	v_and_b32_e32 v11, 0xffff0000, v20
	v_mul_f32_e32 v10, 0xbfb8aa3b, v10
	v_mul_f32_e32 v11, 0xbfb8aa3b, v11
	v_exp_f32_e32 v10, v10
	v_exp_f32_e32 v11, v11
	v_cvt_pk_bf16_f32 v6, v14, v15
	v_cvt_pk_bf16_f32 v7, v12, v24
	v_cvt_pk_bf16_f32 v9, v13, v9
	global_store_dwordx4 v[18:19], v[6:9], off offset:32
	v_and_b32_e32 v12, 0xffff0000, v21
	s_nop 0
	v_and_b32_e32 v8, 0xffff0000, v2
	v_pk_add_f32 v[6:7], v[10:11], 1.0 op_sel_hi:[1,0]
	v_lshlrev_b32_e32 v2, 16, v2
	v_lshlrev_b32_e32 v11, 16, v21
	v_rcp_f32_e32 v9, v7
	s_nop 0
	v_mul_f32_e32 v10, v8, v9
	v_mul_f32_e32 v8, 0xbfb8aa3b, v11
	v_mul_f32_e32 v9, 0xbfb8aa3b, v12
	v_exp_f32_e32 v8, v8
	v_exp_f32_e32 v9, v9
	v_and_b32_e32 v11, 0xffff0000, v3
	v_pk_add_f32 v[8:9], v[8:9], 1.0 op_sel_hi:[1,0]
	v_rcp_f32_e32 v7, v6
	s_nop 0
	v_mul_f32_e32 v14, v2, v7
	v_lshlrev_b32_e32 v6, 16, v3
	v_rcp_f32_e32 v2, v9
	s_nop 0
	v_mul_f32_e32 v9, v11, v2
	v_and_b32_e32 v13, 0xffff0000, v23
	v_lshlrev_b32_e32 v2, 16, v22
	v_and_b32_e32 v3, 0xffff0000, v22
	v_mul_f32_e32 v2, 0xbfb8aa3b, v2
	v_mul_f32_e32 v3, 0xbfb8aa3b, v3
	v_exp_f32_e32 v2, v2
	v_exp_f32_e32 v3, v3
	v_rcp_f32_e32 v7, v8
	s_nop 0
	v_mul_f32_e32 v8, v6, v7
	v_and_b32_e32 v6, 0xffff0000, v4
	v_pk_add_f32 v[2:3], v[2:3], 1.0 op_sel_hi:[1,0]
	v_lshlrev_b32_e32 v4, 16, v4
	v_lshlrev_b32_e32 v12, 16, v23
	v_rcp_f32_e32 v7, v3
	s_nop 0
	v_mul_f32_e32 v11, v6, v7
	v_mul_f32_e32 v6, 0xbfb8aa3b, v12
	v_mul_f32_e32 v7, 0xbfb8aa3b, v13
	v_exp_f32_e32 v6, v6
	v_exp_f32_e32 v7, v7
	v_and_b32_e32 v12, 0xffff0000, v5
	v_pk_add_f32 v[6:7], v[6:7], 1.0 op_sel_hi:[1,0]
	v_rcp_f32_e32 v3, v2
	s_nop 0
	v_mul_f32_e32 v4, v4, v3
	v_lshlrev_b32_e32 v2, 16, v5
	v_rcp_f32_e32 v3, v7
	s_nop 0
	v_mul_f32_e32 v5, v12, v3
	v_cvt_pk_bf16_f32 v4, v4, v11
	v_rcp_f32_e32 v3, v6
	s_nop 0
	v_mul_f32_e32 v6, v2, v3
	v_cvt_pk_bf16_f32 v2, v14, v10
	v_cvt_pk_bf16_f32 v3, v8, v9
	v_cvt_pk_bf16_f32 v5, v6, v5
	global_store_dwordx4 v[18:19], v[2:5], off offset:48
	s_mov_b64 s[26:27], 0

; DI unsigned pk2(float a, float b) { fl2_t f = {a, b}; bf2_t r = __builtin_convertvector(f, bf2_t); return __builtin_bit_cast(unsigned, r); }
; DI void phase2(const Params& p, char* lds) {
;     ...
;       const int j = nt - 12, row = tid & 127, hf = tid >> 7;
;       bfr* dst = (bfr*)(ws + WS_Z) + (size_t)(t0h + row) * 512 + j * 64 + hf * 32;
; #pragma unroll
;       for (int q = 0; q < 4; ++q) {
;         float z[8];
; #pragma unroll
;         for (int u = 0; u < 2; ++u) {
;           float4 a = cs4(Cs, row, hf * 32 + q * 8 + u * 4);
;           float4 g = cs4(Cs, row, 64 + hf * 32 + q * 8 + u * 4);
;           z[u * 4 + 0] = a.x / (1.f + __expf(-g.x)); z[u * 4 + 1] = a.y / (1.f + __expf(-g.y));
;           z[u * 4 + 2] = a.z / (1.f + __expf(-g.z)); z[u * 4 + 3] = a.w / (1.f + __expf(-g.w));
;         }
;         u32x4 o; o[0] = pk2(z[0], z[1]); o[1] = pk2(z[2], z[3]); o[2] = pk2(z[4], z[5]); o[3] = pk2(z[6], z[7]);
;         *(u32x4*)(dst + q * 8) = o;
;       }
.LBB0_131:
	s_cmp_gt_u32 s3, 11
	s_cbranch_scc0 .LBB0_133
	v_add_u32_e32 v2, s44, v166
	ds_read_b128 v[20:23], v167 offset:384
	v_ashrrev_i32_e32 v3, 31, v2
	v_lshlrev_b64 v[2:3], 10, v[2:3]
	s_lshl_b32 s8, s45, 6
	v_lshl_add_u64 v[2:3], s[14:15], 0, v[2:3]
	s_addk_i32 s8, 0xfd00
	v_lshl_add_u64 v[2:3], s[8:9], 1, v[2:3]
	v_lshlrev_b32_e32 v4, 1, v156
	v_mov_b32_e32 v5, v151
	v_lshl_add_u64 v[18:19], v[2:3], 0, v[4:5]
	s_waitcnt lgkmcnt(0)
	v_lshlrev_b32_e32 v2, 16, v20
	v_and_b32_e32 v3, 0xffff0000, v20
	v_mul_f32_e32 v2, 0xbfb8aa3b, v2
	v_exp_f32_e32 v28, v2
	v_mul_f32_e32 v2, 0xbfb8aa3b, v3
	v_exp_f32_e32 v29, v2
	ds_read_b128 v[14:17], v167 offset:256
	ds_read_b128 v[10:13], v167 offset:272
	ds_read_b128 v[24:27], v167 offset:400
	v_lshlrev_b32_e32 v32, 16, v21
	v_and_b32_e32 v21, 0xffff0000, v21
	s_waitcnt lgkmcnt(2)
	v_and_b32_e32 v20, 0xffff0000, v14
	v_pk_add_f32 v[28:29], v[28:29], 1.0 op_sel_hi:[1,0]
	v_lshlrev_b32_e32 v14, 16, v14
	v_mul_f32_e32 v21, 0xbfb8aa3b, v21
	v_exp_f32_e32 v21, v21
	ds_read_b128 v[6:9], v167 offset:288
	ds_read_b128 v[2:5], v167 offset:304
	v_rcp_f32_e32 v30, v29
	s_nop 0
	v_mul_f32_e32 v29, v20, v30
	v_mul_f32_e32 v20, 0xbfb8aa3b, v32
	v_exp_f32_e32 v20, v20
	v_and_b32_e32 v32, 0xffff0000, v15
	v_pk_add_f32 v[20:21], v[20:21], 1.0 op_sel_hi:[1,0]
	v_rcp_f32_e32 v30, v28
	s_nop 0
	v_mul_f32_e32 v28, v14, v30
	v_lshlrev_b32_e32 v30, 16, v15
	v_rcp_f32_e32 v14, v21
	s_nop 0
	v_mul_f32_e32 v32, v32, v14
	v_lshlrev_b32_e32 v14, 16, v22
	v_and_b32_e32 v15, 0xffff0000, v22
	v_mul_f32_e32 v14, 0xbfb8aa3b, v14
	v_mul_f32_e32 v15, 0xbfb8aa3b, v15
	v_exp_f32_e32 v14, v14
	v_exp_f32_e32 v15, v15
	v_rcp_f32_e32 v21, v20
	s_nop 0
	v_mul_f32_e32 v22, v30, v21
	v_and_b32_e32 v20, 0xffff0000, v16
	v_pk_add_f32 v[14:15], v[14:15], 1.0 op_sel_hi:[1,0]
	v_lshlrev_b32_e32 v16, 16, v16
	v_lshlrev_b32_e32 v31, 16, v23
	v_and_b32_e32 v23, 0xffff0000, v23
	v_rcp_f32_e32 v21, v15
	s_nop 0
	v_mul_f32_e32 v30, v20, v21
	v_mul_f32_e32 v20, 0xbfb8aa3b, v31
	v_mul_f32_e32 v21, 0xbfb8aa3b, v23
	v_exp_f32_e32 v20, v20
	v_exp_f32_e32 v21, v21
	v_and_b32_e32 v23, 0xffff0000, v17
	v_pk_add_f32 v[20:21], v[20:21], 1.0 op_sel_hi:[1,0]
	v_rcp_f32_e32 v15, v14
	s_nop 0
	v_mul_f32_e32 v16, v16, v15
	v_lshlrev_b32_e32 v14, 16, v17
	v_rcp_f32_e32 v15, v21
	s_nop 0
	v_mul_f32_e32 v17, v23, v15
	v_cvt_pk_bf16_f32 v16, v16, v30
	v_rcp_f32_e32 v15, v20
	s_nop 0
	v_mul_f32_e32 v23, v14, v15
	s_waitcnt lgkmcnt(2)
	v_lshlrev_b32_e32 v20, 16, v24
	v_and_b32_e32 v21, 0xffff0000, v24
	v_mul_f32_e32 v20, 0xbfb8aa3b, v20
	v_mul_f32_e32 v21, 0xbfb8aa3b, v21
	v_exp_f32_e32 v20, v20
	v_exp_f32_e32 v21, v21
	v_cvt_pk_bf16_f32 v14, v28, v29
	v_cvt_pk_bf16_f32 v15, v22, v32
	v_cvt_pk_bf16_f32 v17, v23, v17
	global_store_dwordx4 v[18:19], v[14:17], off
	v_and_b32_e32 v22, 0xffff0000, v25
	s_nop 0
	v_and_b32_e32 v16, 0xffff0000, v10
	v_pk_add_f32 v[14:15], v[20:21], 1.0 op_sel_hi:[1,0]
	v_lshlrev_b32_e32 v21, 16, v25
	v_lshlrev_b32_e32 v10, 16, v10
	v_rcp_f32_e32 v17, v15
	s_nop 0
	v_mul_f32_e32 v20, v16, v17
	v_mul_f32_e32 v16, 0xbfb8aa3b, v21
	v_mul_f32_e32 v17, 0xbfb8aa3b, v22
	v_exp_f32_e32 v16, v16
	v_exp_f32_e32 v17, v17
	v_and_b32_e32 v21, 0xffff0000, v11
	v_pk_add_f32 v[16:17], v[16:17], 1.0 op_sel_hi:[1,0]
	v_rcp_f32_e32 v15, v14
	s_nop 0
	v_mul_f32_e32 v24, v10, v15
	v_lshlrev_b32_e32 v14, 16, v11
	v_rcp_f32_e32 v10, v17
	s_nop 0
	v_mul_f32_e32 v17, v21, v10
	v_and_b32_e32 v23, 0xffff0000, v27
	v_lshlrev_b32_e32 v10, 16, v26
	v_and_b32_e32 v11, 0xffff0000, v26
	v_mul_f32_e32 v10, 0xbfb8aa3b, v10
	v_mul_f32_e32 v11, 0xbfb8aa3b, v11
	v_exp_f32_e32 v10, v10
	v_exp_f32_e32 v11, v11
	v_rcp_f32_e32 v15, v16
	s_nop 0
	v_mul_f32_e32 v16, v14, v15
	v_and_b32_e32 v14, 0xffff0000, v12
	v_pk_add_f32 v[10:11], v[10:11], 1.0 op_sel_hi:[1,0]
	v_lshlrev_b32_e32 v22, 16, v27
	v_lshlrev_b32_e32 v12, 16, v12
	v_rcp_f32_e32 v15, v11
	s_nop 0
	v_mul_f32_e32 v21, v14, v15
	v_mul_f32_e32 v14, 0xbfb8aa3b, v22
	v_mul_f32_e32 v15, 0xbfb8aa3b, v23
	v_exp_f32_e32 v14, v14
	v_exp_f32_e32 v15, v15
	v_and_b32_e32 v22, 0xffff0000, v13
	v_pk_add_f32 v[14:15], v[14:15], 1.0 op_sel_hi:[1,0]
	v_rcp_f32_e32 v11, v10
	s_nop 0
	v_mul_f32_e32 v26, v12, v11
	v_lshlrev_b32_e32 v10, 16, v13
	v_rcp_f32_e32 v11, v15
	s_nop 0
	v_mul_f32_e32 v27, v22, v11
	v_rcp_f32_e32 v11, v14
	s_nop 0
	v_mul_f32_e32 v28, v10, v11
	ds_read_b128 v[10:13], v167 offset:416
	v_cvt_pk_bf16_f32 v15, v16, v17
	v_cvt_pk_bf16_f32 v14, v24, v20
	v_cvt_pk_bf16_f32 v16, v26, v21
	ds_read_b128 v[20:23], v167 offset:432
	s_waitcnt lgkmcnt(1)
; DI unsigned pk2(float a, float b) { fl2_t f = {a, b}; bf2_t r = __builtin_convertvector(f, bf2_t); return __builtin_bit_cast(unsigned, r); }
; DI void phase2(const Params& p, char* lds) {
;     ...
;       const int j = nt - 12, row = tid & 127, hf = tid >> 7;
;       bfr* dst = (bfr*)(ws + WS_Z) + (size_t)(t0h + row) * 512 + j * 64 + hf * 32;
; #pragma unroll
;       for (int q = 0; q < 4; ++q) {
;         float z[8];
; #pragma unroll
;         for (int u = 0; u < 2; ++u) {
;           float4 a = cs4(Cs, row, hf * 32 + q * 8 + u * 4);
;           float4 g = cs4(Cs, row, 64 + hf * 32 + q * 8 + u * 4);
;           z[u * 4 + 0] = a.x / (1.f + __expf(-g.x)); z[u * 4 + 1] = a.y / (1.f + __expf(-g.y));
;           z[u * 4 + 2] = a.z / (1.f + __expf(-g.z)); z[u * 4 + 3] = a.w / (1.f + __expf(-g.w));
;         }
;         u32x4 o; o[0] = pk2(z[0], z[1]); o[1] = pk2(z[2], z[3]); o[2] = pk2(z[4], z[5]); o[3] = pk2(z[6], z[7]);
;         *(u32x4*)(dst + q * 8) = o;
;       }
	v_lshlrev_b32_e32 v17, 16, v10
	v_and_b32_e32 v10, 0xffff0000, v10
	v_mul_f32_e32 v17, 0xbfb8aa3b, v17
	v_mul_f32_e32 v10, 0xbfb8aa3b, v10
	v_exp_f32_e32 v24, v17
	v_exp_f32_e32 v25, v10
	v_cvt_pk_bf16_f32 v17, v28, v27
	global_store_dwordx4 v[18:19], v[14:17], off offset:16
	v_and_b32_e32 v10, 0xffff0000, v6
	v_lshlrev_b32_e32 v6, 16, v6
	v_pk_add_f32 v[14:15], v[24:25], 1.0 op_sel_hi:[1,0]
	v_lshlrev_b32_e32 v24, 16, v11
	v_and_b32_e32 v11, 0xffff0000, v11
	v_mul_f32_e32 v11, 0xbfb8aa3b, v11
	v_exp_f32_e32 v11, v11
	v_rcp_f32_e32 v16, v15
	s_nop 0
	v_mul_f32_e32 v15, v10, v16
	v_mul_f32_e32 v10, 0xbfb8aa3b, v24
	v_exp_f32_e32 v10, v10
	v_and_b32_e32 v24, 0xffff0000, v7
	v_pk_add_f32 v[10:11], v[10:11], 1.0 op_sel_hi:[1,0]
	v_rcp_f32_e32 v16, v14
	s_nop 0
	v_mul_f32_e32 v14, v6, v16
	v_lshlrev_b32_e32 v16, 16, v7
	v_rcp_f32_e32 v6, v11
	s_nop 0
	v_mul_f32_e32 v24, v24, v6
	v_lshlrev_b32_e32 v6, 16, v12
	v_and_b32_e32 v7, 0xffff0000, v12
	v_mul_f32_e32 v6, 0xbfb8aa3b, v6
	v_mul_f32_e32 v7, 0xbfb8aa3b, v7
	v_exp_f32_e32 v6, v6
	v_exp_f32_e32 v7, v7
	v_rcp_f32_e32 v11, v10
	s_nop 0
	v_mul_f32_e32 v12, v16, v11
	v_and_b32_e32 v10, 0xffff0000, v8
	v_pk_add_f32 v[6:7], v[6:7], 1.0 op_sel_hi:[1,0]
	v_lshlrev_b32_e32 v8, 16, v8
	v_lshlrev_b32_e32 v17, 16, v13
	v_and_b32_e32 v13, 0xffff0000, v13
	v_rcp_f32_e32 v11, v7
	s_nop 0
	v_mul_f32_e32 v16, v10, v11
	v_mul_f32_e32 v10, 0xbfb8aa3b, v17
	v_mul_f32_e32 v11, 0xbfb8aa3b, v13
	v_exp_f32_e32 v10, v10
	v_exp_f32_e32 v11, v11
	v_and_b32_e32 v13, 0xffff0000, v9
	v_pk_add_f32 v[10:11], v[10:11], 1.0 op_sel_hi:[1,0]
	v_rcp_f32_e32 v7, v6
	s_nop 0
	v_mul_f32_e32 v8, v8, v7
	v_lshlrev_b32_e32 v6, 16, v9
	v_rcp_f32_e32 v7, v11
	s_nop 0
	v_mul_f32_e32 v9, v13, v7
	v_cvt_pk_bf16_f32 v8, v8, v16
	v_rcp_f32_e32 v7, v10
	s_nop 0
	v_mul_f32_e32 v13, v6, v7
	s_waitcnt lgkmcnt(0)
	v_lshlrev_b32_e32 v10, 16, v20
	v_and_b32_e32 v11, 0xffff0000, v20
	v_mul_f32_e32 v10, 0xbfb8aa3b, v10
	v_mul_f32_e32 v11, 0xbfb8aa3b, v11
	v_exp_f32_e32 v10, v10
	v_exp_f32_e32 v11, v11
	v_cvt_pk_bf16_f32 v6, v14, v15
	v_cvt_pk_bf16_f32 v7, v12, v24
	v_cvt_pk_bf16_f32 v9, v13, v9
	global_store_dwordx4 v[18:19], v[6:9], off offset:32
	v_and_b32_e32 v12, 0xffff0000, v21
	s_nop 0
	v_and_b32_e32 v8, 0xffff0000, v2
	v_pk_add_f32 v[6:7], v[10:11], 1.0 op_sel_hi:[1,0]
	v_lshlrev_b32_e32 v2, 16, v2
	v_lshlrev_b32_e32 v11, 16, v21
	v_rcp_f32_e32 v9, v7
	s_nop 0
	v_mul_f32_e32 v10, v8, v9
	v_mul_f32_e32 v8, 0xbfb8aa3b, v11
	v_mul_f32_e32 v9, 0xbfb8aa3b, v12
	v_exp_f32_e32 v8, v8
	v_exp_f32_e32 v9, v9
	v_and_b32_e32 v11, 0xffff0000, v3
	v_pk_add_f32 v[8:9], v[8:9], 1.0 op_sel_hi:[1,0]
	v_rcp_f32_e32 v7, v6
	s_nop 0
	v_mul_f32_e32 v14, v2, v7
	v_lshlrev_b32_e32 v6, 16, v3
	v_rcp_f32_e32 v2, v9
	s_nop 0
	v_mul_f32_e32 v9, v11, v2
	v_and_b32_e32 v13, 0xffff0000, v23
	v_lshlrev_b32_e32 v2, 16, v22
	v_and_b32_e32 v3, 0xffff0000, v22
	v_mul_f32_e32 v2, 0xbfb8aa3b, v2
	v_mul_f32_e32 v3, 0xbfb8aa3b, v3
	v_exp_f32_e32 v2, v2
	v_exp_f32_e32 v3, v3
	v_rcp_f32_e32 v7, v8
	s_nop 0
	v_mul_f32_e32 v8, v6, v7
	v_and_b32_e32 v6, 0xffff0000, v4
	v_pk_add_f32 v[2:3], v[2:3], 1.0 op_sel_hi:[1,0]
	v_lshlrev_b32_e32 v4, 16, v4
	v_lshlrev_b32_e32 v12, 16, v23
	v_rcp_f32_e32 v7, v3
	s_nop 0
	v_mul_f32_e32 v11, v6, v7
	v_mul_f32_e32 v6, 0xbfb8aa3b, v12
	v_mul_f32_e32 v7, 0xbfb8aa3b, v13
	v_exp_f32_e32 v6, v6
	v_exp_f32_e32 v7, v7
	v_and_b32_e32 v12, 0xffff0000, v5
	v_pk_add_f32 v[6:7], v[6:7], 1.0 op_sel_hi:[1,0]
	v_rcp_f32_e32 v3, v2
	s_nop 0
	v_mul_f32_e32 v4, v4, v3
	v_lshlrev_b32_e32 v2, 16, v5
	v_rcp_f32_e32 v3, v7
	s_nop 0
	v_mul_f32_e32 v5, v12, v3
	v_cvt_pk_bf16_f32 v4, v4, v11
	v_rcp_f32_e32 v3, v6
	s_nop 0
	v_mul_f32_e32 v6, v2, v3
	v_cvt_pk_bf16_f32 v2, v14, v10
	v_cvt_pk_bf16_f32 v3, v8, v9
	v_cvt_pk_bf16_f32 v5, v6, v5
	global_store_dwordx4 v[18:19], v[2:5], off offset:48
	s_mov_b64 s[26:27], 0

; DI unsigned pk2(float a, float b) { fl2_t f = {a, b}; bf2_t r = __builtin_convertvector(f, bf2_t); return __builtin_bit_cast(unsigned, r); }
; DI void conv_item(const Params& p, char* lds, int t0, int tid) {
;     ...
;     __syncthreads();
; #pragma unroll
;     for (int i = 0; i < 8; ++i) {
;       const float s1 = red[(0 * 8 + i) * 2] + red[(1 * 8 + i) * 2] + red[(2 * 8 + i) * 2] + red[(3 * 8 + i) * 2];
;       const float s2 = red[(0 * 8 + i) * 2 + 1] + red[(1 * 8 + i) * 2 + 1] + red[(2 * 8 + i) * 2 + 1] + red[(3 * 8 + i) * 2 + 1];
;       const float mu = s1 * (1.f / 512.f);
;       const float var = fmaxf(s2 * (1.f / 512.f) - mu * mu, 0.f);
;       const float rstd = rsqrtf(var + 1e-6f);
;       float a = (ya[i] - mu) * rstd * gl.x + bl.x, b = (yb[i] - mu) * rstd * gl.y + bl.y;
;       a = a / (1.f + __expf(-a)); b = b / (1.f + __expf(-b));
;       Hu[((size_t)(t0 + ps * 8 + i) * D + 512) / 2 + tid] = pk2(a, b);
;     }
.LBB0_195:
	s_or_b64 exec, exec, s[6:7]
	s_waitcnt lgkmcnt(0)
	s_barrier
	ds_read_b128 v[160:163], v220 offset:63552
	ds_read_b128 v[166:169], v220 offset:63488
	ds_read_b128 v[6:9], v220 offset:63504
	ds_read_b128 v[170:173], v220 offset:63616
	ds_read_b128 v[174:177], v220 offset:63680
	ds_read_b128 v[178:181], v220 offset:63568
	s_waitcnt lgkmcnt(4)
	v_pk_add_f32 v[4:5], v[166:167], v[160:161]
	v_pk_add_f32 v[162:163], v[168:169], v[162:163]
	s_waitcnt lgkmcnt(2)
	v_pk_add_f32 v[4:5], v[4:5], v[170:171]
	v_pk_add_f32 v[162:163], v[162:163], v[172:173]
	s_waitcnt lgkmcnt(1)
	v_pk_add_f32 v[4:5], v[4:5], v[174:175]
	v_pk_add_f32 v[162:163], v[162:163], v[176:177]
	v_pk_mul_f32 v[4:5], v[4:5], s[0:1] op_sel_hi:[1,0]
	v_pk_mul_f32 v[162:163], v[162:163], s[0:1] op_sel_hi:[1,0]
	v_fma_f32 v160, -v4, v4, v5
	v_max_f32_e32 v160, 0, v160
	v_add_f32_e32 v160, 0x358637bd, v160
	v_mul_f32_e32 v161, 0x4b800000, v160
	v_cmp_gt_f32_e32 vcc, s11, v160
	v_pk_add_f32 v[2:3], v[2:3], v[4:5] op_sel_hi:[1,0] neg_lo:[0,1] neg_hi:[0,1]
	v_fma_f32 v168, -v162, v162, v163
	v_cndmask_b32_e32 v160, v160, v161, vcc
	v_rsq_f32_e32 v160, v160
	v_max_f32_e32 v168, 0, v168
	v_add_f32_e32 v168, 0x358637bd, v168
	v_mul_f32_e32 v169, 0x4b800000, v168
	v_mul_f32_e32 v161, 0x45800000, v160
	v_cndmask_b32_e32 v160, v160, v161, vcc
	v_pk_mul_f32 v[2:3], v[2:3], v[160:161] op_sel_hi:[1,0]
	v_pk_add_f32 v[156:157], v[156:157], v[162:163] op_sel_hi:[1,0] neg_lo:[0,1] neg_hi:[0,1]
	v_pk_fma_f32 v[166:167], v[144:145], v[2:3], v[146:147]
	v_add_u32_e32 v160, s8, v1
	v_mul_f32_e32 v2, 0xbfb8aa3b, v166
	v_mul_f32_e32 v3, 0xbfb8aa3b, v167
	v_exp_f32_e32 v2, v2
	v_exp_f32_e32 v3, v3
	ds_read_b128 v[182:185], v220 offset:63632
	ds_read_b128 v[186:189], v220 offset:63696
	s_waitcnt lgkmcnt(2)
	v_pk_add_f32 v[6:7], v[6:7], v[178:179]
	v_pk_add_f32 v[170:171], v[2:3], 1.0 op_sel_hi:[1,0]
	v_pk_add_f32 v[8:9], v[8:9], v[180:181]
	s_waitcnt lgkmcnt(1)
	v_pk_add_f32 v[6:7], v[6:7], v[182:183]
	v_pk_add_f32 v[8:9], v[8:9], v[184:185]
	s_waitcnt lgkmcnt(0)
	v_pk_add_f32 v[6:7], v[6:7], v[186:187]
	v_rcp_f32_e32 v161, v171
	s_nop 0
	v_mul_f32_e32 v161, v167, v161
	v_cmp_gt_f32_e64 s[6:7], s11, v168
	v_cndmask_b32_e64 v168, v168, v169, s[6:7]
	v_rsq_f32_e32 v168, v168
	v_rcp_f32_e32 v167, v170
	s_nop 0
	v_mul_f32_e32 v167, v166, v167
	v_mul_f32_e32 v166, 0x45800000, v168
	v_cndmask_b32_e64 v166, v168, v166, s[6:7]
	v_pk_mul_f32 v[156:157], v[156:157], v[166:167] op_sel_hi:[1,0]
	v_cvt_pk_bf16_f32 v168, v167, v161
	v_pk_fma_f32 v[156:157], v[144:145], v[156:157], v[146:147]
	v_ashrrev_i32_e32 v161, 31, v160
	v_mul_f32_e32 v162, 0xbfb8aa3b, v156
	v_mul_f32_e32 v163, 0xbfb8aa3b, v157
	v_exp_f32_e32 v162, v162
	v_exp_f32_e32 v163, v163
	v_lshlrev_b64 v[166:167], 11, v[160:161]
	v_and_b32_e32 v166, 0xffffc000, v166
	v_lshl_add_u64 v[166:167], v[78:79], 0, v[166:167]
	v_pk_add_f32 v[162:163], v[162:163], 1.0 op_sel_hi:[1,0]
	global_store_dword v[166:167], v168, off
	v_pk_mul_f32 v[6:7], v[6:7], s[0:1] op_sel_hi:[1,0]
	v_pk_add_f32 v[8:9], v[8:9], v[188:189]
	ds_read_b128 v[2:5], v220 offset:63520
	v_rcp_f32_e32 v161, v163
	s_nop 0
	v_mul_f32_e32 v161, v157, v161
	v_pk_mul_f32 v[8:9], v[8:9], s[0:1] op_sel_hi:[1,0]
	v_fma_f32 v166, -v6, v6, v7
	v_max_f32_e32 v166, 0, v166
	v_add_f32_e32 v166, 0x358637bd, v166
	v_mul_f32_e32 v167, 0x4b800000, v166
	v_cmp_gt_f32_e64 s[6:7], s11, v166
	v_rcp_f32_e32 v157, v162
	s_nop 0
	v_mul_f32_e32 v162, v156, v157
	v_cndmask_b32_e64 v166, v166, v167, s[6:7]
	v_rsq_f32_e32 v166, v166
	v_pk_add_f32 v[6:7], v[158:159], v[6:7] op_sel_hi:[1,0] neg_lo:[0,1] neg_hi:[0,1]
	v_cvt_pk_bf16_f32 v161, v162, v161
	v_add_u32_e32 v158, 1, v160
	v_mul_f32_e32 v156, 0x45800000, v166
	v_cndmask_b32_e64 v156, v166, v156, s[6:7]
	v_pk_mul_f32 v[6:7], v[6:7], v[156:157] op_sel_hi:[1,0]
	v_ashrrev_i32_e32 v159, 31, v158
	v_pk_fma_f32 v[6:7], v[144:145], v[6:7], v[146:147]
	v_lshlrev_b64 v[158:159], 11, v[158:159]
	v_mul_f32_e32 v156, 0xbfb8aa3b, v6
	v_mul_f32_e32 v157, 0xbfb8aa3b, v7
	v_exp_f32_e32 v156, v156
	v_exp_f32_e32 v157, v157
	v_lshl_add_u64 v[158:159], v[78:79], 0, v[158:159]
	global_store_dword v[158:159], v161, off
	s_add_i32 s8, s8, 8
	v_pk_add_f32 v[156:157], v[156:157], 1.0 op_sel_hi:[1,0]
	v_add_u32_e32 v238, 0x2000, v238
	s_cmp_lg_u32 s8, 32
	v_rcp_f32_e32 v158, v157
	s_nop 0
	v_mul_f32_e32 v157, v7, v158
	v_fma_f32 v159, -v8, v8, v9
	v_max_f32_e32 v159, 0, v159
	v_add_f32_e32 v159, 0x358637bd, v159
	v_mul_f32_e32 v161, 0x4b800000, v159
	v_cmp_gt_f32_e64 s[6:7], s11, v159
	v_rcp_f32_e32 v7, v156
	s_nop 0
	v_mul_f32_e32 v156, v6, v7
	v_cndmask_b32_e64 v159, v159, v161, s[6:7]
	v_rsq_f32_e32 v159, v159
	v_pk_add_f32 v[8:9], v[164:165], v[8:9] op_sel_hi:[1,0] neg_lo:[0,1] neg_hi:[0,1]
	v_cvt_pk_bf16_f32 v156, v156, v157
	v_mul_f32_e32 v6, 0x45800000, v159
	v_cndmask_b32_e64 v6, v159, v6, s[6:7]
	v_pk_mul_f32 v[6:7], v[8:9], v[6:7] op_sel_hi:[1,0]
	v_add_u32_e32 v8, 2, v160
	v_pk_fma_f32 v[182:183], v[144:145], v[6:7], v[146:147]
	v_ashrrev_i32_e32 v9, 31, v8
	v_mul_f32_e32 v6, 0xbfb8aa3b, v182
	v_mul_f32_e32 v7, 0xbfb8aa3b, v183
	v_exp_f32_e32 v6, v6
	v_exp_f32_e32 v7, v7
	s_nop 0
	v_pk_add_f32 v[184:185], v[6:7], 1.0 op_sel_hi:[1,0]
	s_nop 0
	v_lshlrev_b64 v[6:7], 11, v[8:9]
	v_lshl_add_u64 v[6:7], v[78:79], 0, v[6:7]
	global_store_dword v[6:7], v156, off
	v_rcp_f32_e32 v6, v185
	s_nop 0
	v_mul_f32_e32 v183, v183, v6
	ds_read_b128 v[6:9], v220 offset:63584
	ds_read_b128 v[156:159], v220 offset:63648
	ds_read_b128 v[162:165], v220 offset:63712
	ds_read_b128 v[166:169], v220 offset:63536
	ds_read_b128 v[170:173], v220 offset:63600
	s_waitcnt lgkmcnt(4)
; DI unsigned pk2(float a, float b) { fl2_t f = {a, b}; bf2_t r = __builtin_convertvector(f, bf2_t); return __builtin_bit_cast(unsigned, r); }
; DI void conv_item(const Params& p, char* lds, int t0, int tid) {
;     ...
; #pragma unroll
;     for (int i = 0; i < 8; ++i) {
;       const float s1 = red[(0 * 8 + i) * 2] + red[(1 * 8 + i) * 2] + red[(2 * 8 + i) * 2] + red[(3 * 8 + i) * 2];
;       const float s2 = red[(0 * 8 + i) * 2 + 1] + red[(1 * 8 + i) * 2 + 1] + red[(2 * 8 + i) * 2 + 1] + red[(3 * 8 + i) * 2 + 1];
;       const float mu = s1 * (1.f / 512.f);
;       const float var = fmaxf(s2 * (1.f / 512.f) - mu * mu, 0.f);
;       const float rstd = rsqrtf(var + 1e-6f);
;       float a = (ya[i] - mu) * rstd * gl.x + bl.x, b = (yb[i] - mu) * rstd * gl.y + bl.y;
;       a = a / (1.f + __expf(-a)); b = b / (1.f + __expf(-b));
;       Hu[((size_t)(t0 + ps * 8 + i) * D + 512) / 2 + tid] = pk2(a, b);
;     }
;     __syncthreads();
	v_pk_add_f32 v[2:3], v[2:3], v[6:7]
	v_pk_add_f32 v[4:5], v[4:5], v[8:9]
	s_waitcnt lgkmcnt(3)
	v_pk_add_f32 v[2:3], v[2:3], v[156:157]
	v_pk_add_f32 v[4:5], v[4:5], v[158:159]
	s_waitcnt lgkmcnt(2)
	v_pk_add_f32 v[2:3], v[2:3], v[162:163]
	v_pk_add_f32 v[4:5], v[4:5], v[164:165]
	v_pk_mul_f32 v[2:3], v[2:3], s[0:1] op_sel_hi:[1,0]
	v_pk_mul_f32 v[4:5], v[4:5], s[0:1] op_sel_hi:[1,0]
	v_fma_f32 v6, -v2, v2, v3
	v_max_f32_e32 v6, 0, v6
	v_add_f32_e32 v6, 0x358637bd, v6
	v_mul_f32_e32 v7, 0x4b800000, v6
	v_cmp_gt_f32_e64 s[6:7], s11, v6
	v_pk_add_f32 v[2:3], v[148:149], v[2:3] op_sel_hi:[1,0] neg_lo:[0,1] neg_hi:[0,1]
	v_add_u32_e32 v148, 3, v160
	v_cndmask_b32_e64 v6, v6, v7, s[6:7]
	v_rsq_f32_e32 v6, v6
	v_rcp_f32_e32 v7, v184
	s_nop 0
	v_mul_f32_e32 v156, v182, v7
	v_ashrrev_i32_e32 v149, 31, v148
	v_mul_f32_e32 v7, 0x45800000, v6
	v_cndmask_b32_e64 v6, v6, v7, s[6:7]
	v_pk_mul_f32 v[2:3], v[2:3], v[6:7] op_sel_hi:[1,0]
	v_lshlrev_b64 v[148:149], 11, v[148:149]
	v_pk_fma_f32 v[2:3], v[144:145], v[2:3], v[146:147]
	v_cvt_pk_bf16_f32 v156, v156, v183
	v_mul_f32_e32 v6, 0xbfb8aa3b, v2
	v_mul_f32_e32 v7, 0xbfb8aa3b, v3
	v_exp_f32_e32 v6, v6
	v_exp_f32_e32 v7, v7
	v_lshl_add_u64 v[148:149], v[78:79], 0, v[148:149]
	global_store_dword v[148:149], v156, off
	v_fma_f32 v8, -v4, v4, v5
	v_pk_add_f32 v[6:7], v[6:7], 1.0 op_sel_hi:[1,0]
	v_max_f32_e32 v8, 0, v8
	v_add_f32_e32 v8, 0x358637bd, v8
	v_mul_f32_e32 v9, 0x4b800000, v8
	v_pk_add_f32 v[4:5], v[150:151], v[4:5] op_sel_hi:[1,0] neg_lo:[0,1] neg_hi:[0,1]
	v_rcp_f32_e32 v148, v7
	s_nop 0
	v_mul_f32_e32 v7, v3, v148
	v_cmp_gt_f32_e64 s[6:7], s11, v8
	v_cndmask_b32_e64 v8, v8, v9, s[6:7]
	v_rsq_f32_e32 v8, v8
	v_rcp_f32_e32 v3, v6
	s_nop 0
	v_mul_f32_e32 v6, v2, v3
	v_mul_f32_e32 v2, 0x45800000, v8
	v_cndmask_b32_e64 v2, v8, v2, s[6:7]
	v_pk_mul_f32 v[2:3], v[4:5], v[2:3] op_sel_hi:[1,0]
	v_cvt_pk_bf16_f32 v8, v6, v7
	v_pk_fma_f32 v[2:3], v[144:145], v[2:3], v[146:147]
	v_add_u32_e32 v6, 4, v160
	v_mul_f32_e32 v4, 0xbfb8aa3b, v2
	v_mul_f32_e32 v5, 0xbfb8aa3b, v3
	v_exp_f32_e32 v4, v4
	v_exp_f32_e32 v5, v5
	v_ashrrev_i32_e32 v7, 31, v6
	v_lshlrev_b64 v[6:7], 11, v[6:7]
	v_lshl_add_u64 v[6:7], v[78:79], 0, v[6:7]
	v_pk_add_f32 v[4:5], v[4:5], 1.0 op_sel_hi:[1,0]
	global_store_dword v[6:7], v8, off
	ds_read_b128 v[174:177], v220 offset:63664
	ds_read_b128 v[178:181], v220 offset:63728
	v_rcp_f32_e32 v6, v5
	s_nop 0
	v_mul_f32_e32 v148, v3, v6
	s_waitcnt lgkmcnt(2)
	v_pk_add_f32 v[6:7], v[166:167], v[170:171]
	s_waitcnt lgkmcnt(1)
	v_pk_add_f32 v[6:7], v[6:7], v[174:175]
	s_waitcnt lgkmcnt(0)
	v_pk_add_f32 v[6:7], v[6:7], v[178:179]
	v_rcp_f32_e32 v3, v4
	s_nop 0
	v_mul_f32_e32 v9, v2, v3
	v_pk_mul_f32 v[6:7], v[6:7], s[0:1] op_sel_hi:[1,0]
	s_nop 0
	v_fma_f32 v8, -v6, v6, v7
	v_max_f32_e32 v8, 0, v8
	v_add_f32_e32 v8, 0x358637bd, v8
	v_mul_f32_e32 v149, 0x4b800000, v8
	v_cmp_gt_f32_e64 s[6:7], s11, v8
	v_pk_add_f32 v[4:5], v[152:153], v[6:7] op_sel_hi:[1,0] neg_lo:[0,1] neg_hi:[0,1]
	v_add_u32_e32 v6, 5, v160
	v_cndmask_b32_e64 v8, v8, v149, s[6:7]
	v_rsq_f32_e32 v8, v8
	v_ashrrev_i32_e32 v7, 31, v6
	v_lshlrev_b64 v[6:7], 11, v[6:7]
	v_lshl_add_u64 v[6:7], v[78:79], 0, v[6:7]
	v_mul_f32_e32 v2, 0x45800000, v8
	v_cndmask_b32_e64 v2, v8, v2, s[6:7]
	v_pk_mul_f32 v[2:3], v[4:5], v[2:3] op_sel_hi:[1,0]
	v_cvt_pk_bf16_f32 v8, v9, v148
	v_pk_fma_f32 v[2:3], v[144:145], v[2:3], v[146:147]
	global_store_dword v[6:7], v8, off
	v_mul_f32_e32 v4, 0xbfb8aa3b, v2
	v_mul_f32_e32 v5, 0xbfb8aa3b, v3
	v_exp_f32_e32 v4, v4
	v_exp_f32_e32 v5, v5
	s_nop 0
	v_pk_add_f32 v[4:5], v[4:5], 1.0 op_sel_hi:[1,0]
	s_nop 0
	s_nop 0
	v_rcp_f32_e32 v6, v5
	s_nop 0
	v_mul_f32_e32 v148, v3, v6
	v_pk_add_f32 v[6:7], v[168:169], v[172:173]
	v_pk_add_f32 v[6:7], v[6:7], v[176:177]
	v_pk_add_f32 v[6:7], v[6:7], v[180:181]
	v_rcp_f32_e32 v3, v4
	s_nop 0
	v_mul_f32_e32 v9, v2, v3
	v_pk_mul_f32 v[6:7], v[6:7], s[0:1] op_sel_hi:[1,0]
	s_nop 0
	v_fma_f32 v8, -v6, v6, v7
	v_max_f32_e32 v8, 0, v8
	v_add_f32_e32 v8, 0x358637bd, v8
	v_mul_f32_e32 v149, 0x4b800000, v8
	v_cmp_gt_f32_e64 s[6:7], s11, v8
	v_pk_add_f32 v[4:5], v[154:155], v[6:7] op_sel_hi:[1,0] neg_lo:[0,1] neg_hi:[0,1]
	v_add_u32_e32 v6, 6, v160
	v_cndmask_b32_e64 v8, v8, v149, s[6:7]
	v_rsq_f32_e32 v8, v8
	v_ashrrev_i32_e32 v7, 31, v6
	v_lshlrev_b64 v[6:7], 11, v[6:7]
	v_lshl_add_u64 v[6:7], v[78:79], 0, v[6:7]
	v_mul_f32_e32 v2, 0x45800000, v8
	v_cndmask_b32_e64 v2, v8, v2, s[6:7]
	v_pk_mul_f32 v[2:3], v[4:5], v[2:3] op_sel_hi:[1,0]
	v_cvt_pk_bf16_f32 v8, v9, v148
	v_pk_fma_f32 v[2:3], v[144:145], v[2:3], v[146:147]
	global_store_dword v[6:7], v8, off
	v_mul_f32_e32 v4, 0xbfb8aa3b, v2
	v_mul_f32_e32 v5, 0xbfb8aa3b, v3
	v_exp_f32_e32 v4, v4
	v_exp_f32_e32 v5, v5
	s_nop 0
	v_pk_add_f32 v[4:5], v[4:5], 1.0 op_sel_hi:[1,0]
	s_nop 0
	s_nop 0
	v_rcp_f32_e32 v6, v5
	s_nop 0
	v_mul_f32_e32 v3, v3, v6
	v_rcp_f32_e32 v5, v4
	s_nop 0
	v_mul_f32_e32 v2, v2, v5
	v_cvt_pk_bf16_f32 v4, v2, v3
	v_add_u32_e32 v2, 7, v160
	v_ashrrev_i32_e32 v3, 31, v2
	v_lshlrev_b64 v[2:3], 11, v[2:3]
	v_lshl_add_u64 v[2:3], v[78:79], 0, v[2:3]
	global_store_dword v[2:3], v4, off
	s_barrier
	s_cbranch_scc0 .LBB0_189

; #define MFMA(a, b, c) __builtin_amdgcn_mfma_f32_32x32x16_bf16((a), (b), (c), 0, 0, 0)
; #define WAIT_V(n) asm volatile("s_waitcnt vmcnt(%0)" ::"n"(n) : "memory")
; #define RAW_BARRIER() do { asm volatile("s_waitcnt lgkmcnt(0)" ::: "memory"); __builtin_amdgcn_s_barrier(); } while (0)
; template <typename FA, typename FB, typename FE>
; DI void gemm_tile(char* lds, int K, int astride, int bstride, FA arow, FB brow, FE epi) {
;     ...
;   stage(0, 0); stage(1, 1); stage(2, 2);
;   for (int kt = 0; kt < nk; ++kt) {
;     if (kt + 2 < nk) WAIT_V(8); else if (kt + 1 < nk) WAIT_V(4); else WAIT_V(0);
;     RAW_BARRIER();
;     if (kt + 3 < nk) stage((kt + 3) & 3, kt + 3);
;     const char* sa = lds + (kt & 3) * 32768 + wm * 4096;
;     const char* sb = lds + (kt & 3) * 32768 + 16384 + wn * 8192;
; #pragma unroll
;     for (int ks = 0; ks < 2; ++ks) {
;       bf16x8 a0 = *(const bf16x8*)(sa + foff[ks]), a1 = *(const bf16x8*)(sa + 2048 + foff[ks]);
; #pragma unroll
;       for (int nt = 0; nt < 4; ++nt) {
;         bf16x8 bb = *(const bf16x8*)(sb + nt * 2048 + foff[ks]);
;         acc[0][nt] = MFMA(a0, bb, acc[0][nt]);
;         acc[1][nt] = MFMA(a1, bb, acc[1][nt]);
;       }
;     }
;   }
.Lgm_P6_loop:
	s_and_b32 s25, s24, 0x18000
	s_add_i32 s25, s41, s25
	s_waitcnt vmcnt(4)
	v_lshl_add_u64 v[138:139], v[134:135], 0, v[150:151]
	v_lshl_add_u64 v[140:141], v[130:131], 0, v[150:151]
	s_mov_b32 m0, s25
	s_barrier
	s_add_i32 s42, s24, 0xfffe8000
	s_and_b32 s42, s42, 0x18000
	s_add_i32 s43, s42, s40
	s_or_b32 s42, s42, s27
	v_add_u32_e32 v246, s43, v160
	v_add_u32_e32 v247, s42, v160
	s_waitcnt lgkmcnt(4)
	v_mfma_f32_32x32x16_bf16 v[114:129], v[196:199], v[204:207], v[114:129]
	global_load_lds_dwordx4 v[138:139], off
	s_add_i32 m0, s25, 0x4000
	ds_read_b128 v[220:223], v246
	s_waitcnt lgkmcnt(4)
	v_mfma_f32_32x32x16_bf16 v[50:65], v[200:203], v[204:207], v[50:65]
	v_lshl_add_u64 v[142:143], v[136:137], 0, v[150:151]
	global_load_lds_dwordx4 v[140:141], off
	s_add_i32 m0, s25, 0x400
	ds_read_b128 v[228:231], v247 offset:16384
	s_waitcnt lgkmcnt(4)
	v_mfma_f32_32x32x16_bf16 v[98:113], v[196:199], v[208:211], v[98:113]
	v_lshl_add_u64 v[144:145], v[132:133], 0, v[150:151]
	global_load_lds_dwordx4 v[142:143], off
	s_add_i32 m0, s25, 0x4400
	ds_read_b128 v[224:227], v246 offset:2048
	v_mfma_f32_32x32x16_bf16 v[34:49], v[200:203], v[208:211], v[34:49]
	ds_read_b128 v[232:235], v247 offset:18432
	global_load_lds_dwordx4 v[144:145], off
	s_waitcnt lgkmcnt(5)
	v_mfma_f32_32x32x16_bf16 v[82:97], v[196:199], v[212:215], v[82:97]
	ds_read_b128 v[236:239], v247 offset:20480
	v_lshl_add_u64 v[130:131], v[130:131], 0, s[18:19]
	v_lshl_add_u64 v[132:133], v[132:133], 0, s[18:19]
	v_mfma_f32_32x32x16_bf16 v[18:33], v[200:203], v[212:215], v[18:33]
	ds_read_b128 v[240:243], v247 offset:22528
	v_lshl_add_u64 v[134:135], v[134:135], 0, 64
	v_lshl_add_u64 v[136:137], v[136:137], 0, 64
	s_waitcnt lgkmcnt(6)
	v_mfma_f32_32x32x16_bf16 v[66:81], v[196:199], v[216:219], v[66:81]
	s_add_i32 s42, s24, 0xffff0000
	s_and_b32 s42, s42, 0x18000
	s_add_i32 s43, s42, s40
	v_mfma_f32_32x32x16_bf16 v[2:17], v[200:203], v[216:219], v[2:17]
	s_or_b32 s42, s42, s27
	v_add_u32_e32 v244, s43, v159
	v_add_u32_e32 v245, s42, v159
	s_waitcnt lgkmcnt(4)
	v_mfma_f32_32x32x16_bf16 v[114:129], v[220:223], v[228:231], v[114:129]
	ds_read_b128 v[196:199], v244
	s_waitcnt lgkmcnt(4)
	v_mfma_f32_32x32x16_bf16 v[50:65], v[224:227], v[228:231], v[50:65]
	ds_read_b128 v[204:207], v245 offset:16384
	s_waitcnt lgkmcnt(4)
	v_mfma_f32_32x32x16_bf16 v[98:113], v[220:223], v[232:235], v[98:113]
	ds_read_b128 v[200:203], v244 offset:2048
	v_mfma_f32_32x32x16_bf16 v[34:49], v[224:227], v[232:235], v[34:49]
	ds_read_b128 v[208:211], v245 offset:18432
	s_waitcnt lgkmcnt(5)
	v_mfma_f32_32x32x16_bf16 v[82:97], v[220:223], v[236:239], v[82:97]
	ds_read_b128 v[212:215], v245 offset:20480
	v_mfma_f32_32x32x16_bf16 v[18:33], v[224:227], v[236:239], v[18:33]
	ds_read_b128 v[216:219], v245 offset:22528
	s_waitcnt lgkmcnt(6)
	v_mfma_f32_32x32x16_bf16 v[66:81], v[220:223], v[240:243], v[66:81]
	s_add_i32 s24, s24, 0x8000
	v_mfma_f32_32x32x16_bf16 v[2:17], v[224:227], v[240:243], v[2:17]
	s_cmp_eq_u32 s24, 0x100000
	s_cbranch_scc0 .Lgm_P6_loop
	s_waitcnt vmcnt(8)
	v_add_u32_e32 v138, s40, v159
	s_waitcnt lgkmcnt(0)
	s_barrier
	ds_read_b128 v[130:133], v138 offset:32768
	ds_read_b128 v[138:141], v138 offset:34816
	v_add_u32_e32 v142, s27, v159
	ds_read_b128 v[134:137], v142 offset:49152
	v_add_u32_e32 v143, s27, v160
	s_add_i32 s24, s40, 0x10000
	s_waitcnt lgkmcnt(0)
	v_mfma_f32_32x32x16_bf16 v[114:129], v[130:133], v[134:137], v[114:129]
	s_or_b32 s25, s27, 0x14000
	v_add_u32_e32 v169, s25, v159
	v_add_u32_e32 v182, s24, v160
	v_mfma_f32_32x32x16_bf16 v[50:65], v[138:141], v[134:137], v[50:65]
	ds_read_b128 v[134:137], v142 offset:51200
	s_waitcnt lgkmcnt(0)
	v_mfma_f32_32x32x16_bf16 v[98:113], v[130:133], v[134:137], v[98:113]
	v_mfma_f32_32x32x16_bf16 v[34:49], v[138:141], v[134:137], v[34:49]
	ds_read_b128 v[134:137], v142 offset:53248
	s_waitcnt lgkmcnt(0)
	v_mfma_f32_32x32x16_bf16 v[82:97], v[130:133], v[134:137], v[82:97]
	v_mfma_f32_32x32x16_bf16 v[18:33], v[138:141], v[134:137], v[18:33]
	ds_read_b128 v[134:137], v142 offset:55296
	v_add_u32_e32 v142, s40, v160
	s_add_i32 s40, s40, 0x18000
	v_add_u32_e32 v202, s40, v160
	s_waitcnt lgkmcnt(0)
	v_mfma_f32_32x32x16_bf16 v[66:81], v[130:133], v[134:137], v[66:81]
	ds_read_b128 v[130:133], v142 offset:32768
	v_mfma_f32_32x32x16_bf16 v[2:17], v[138:141], v[134:137], v[2:17]
	ds_read_b128 v[138:141], v142 offset:34816
	ds_read_b128 v[134:137], v143 offset:49152
	v_add_u32_e32 v142, s24, v159
	s_or_b32 s24, s27, 0x1c000
	v_add_u32_e32 v234, s24, v159
	v_add_u32_e32 v226, s24, v160
	s_waitcnt lgkmcnt(0)
	v_mfma_f32_32x32x16_bf16 v[114:129], v[130:133], v[134:137], v[114:129]
	v_mfma_f32_32x32x16_bf16 v[50:65], v[138:141], v[134:137], v[50:65]
	ds_read_b128 v[134:137], v143 offset:51200
	s_waitcnt lgkmcnt(0)
	v_mfma_f32_32x32x16_bf16 v[98:113], v[130:133], v[134:137], v[98:113]
	v_mfma_f32_32x32x16_bf16 v[34:49], v[138:141], v[134:137], v[34:49]
	ds_read_b128 v[134:137], v143 offset:53248
	s_waitcnt lgkmcnt(0)
	v_mfma_f32_32x32x16_bf16 v[82:97], v[130:133], v[134:137], v[82:97]
	v_mfma_f32_32x32x16_bf16 v[18:33], v[138:141], v[134:137], v[18:33]
	ds_read_b128 v[134:137], v143 offset:55296
	s_waitcnt vmcnt(4)
	s_waitcnt lgkmcnt(0)
	s_barrier
; #define MFMA(a, b, c) __builtin_amdgcn_mfma_f32_32x32x16_bf16((a), (b), (c), 0, 0, 0)
; DI unsigned pk2(float a, float b) { fl2_t f = {a, b}; bf2_t r = __builtin_convertvector(f, bf2_t); return __builtin_bit_cast(unsigned, r); }
; #define WAIT_V(n) asm volatile("s_waitcnt vmcnt(%0)" ::"n"(n) : "memory")
; #define RAW_BARRIER() do { asm volatile("s_waitcnt lgkmcnt(0)" ::: "memory"); __builtin_amdgcn_s_barrier(); } while (0)
; template <typename FA, typename FB, typename FE>
; DI void gemm_tile(char* lds, int K, int astride, int bstride, FA arow, FB brow, FE epi) {
;     ...
;   for (int kt = 0; kt < nk; ++kt) {
;     if (kt + 2 < nk) WAIT_V(8); else if (kt + 1 < nk) WAIT_V(4); else WAIT_V(0);
;     RAW_BARRIER();
;     if (kt + 3 < nk) stage((kt + 3) & 3, kt + 3);
;     const char* sa = lds + (kt & 3) * 32768 + wm * 4096;
;     const char* sb = lds + (kt & 3) * 32768 + 16384 + wn * 8192;
; #pragma unroll
;     for (int ks = 0; ks < 2; ++ks) {
;       bf16x8 a0 = *(const bf16x8*)(sa + foff[ks]), a1 = *(const bf16x8*)(sa + 2048 + foff[ks]);
; #pragma unroll
;       for (int nt = 0; nt < 4; ++nt) {
;         bf16x8 bb = *(const bf16x8*)(sb + nt * 2048 + foff[ks]);
;         acc[0][nt] = MFMA(a0, bb, acc[0][nt]);
;         acc[1][nt] = MFMA(a1, bb, acc[1][nt]);
;       }
;     }
;   }
;   RAW_BARRIER();
;   bfr* Cs = (bfr*)lds;
; #pragma unroll
;   for (int mt = 0; mt < 2; ++mt)
; #pragma unroll
;     for (int nt = 0; nt < 4; ++nt)
; #pragma unroll
;       for (int i = 0; i < 16; i += 2) {
;         const int row = wm * 64 + mt * 32 + (i & 3) + 8 * (i >> 2) + 4 * h8;
;         const unsigned pr = pk2(acc[mt][nt][i], acc[mt][nt][i + 1]);
;         Cs[row * CSS + wn * 128 + nt * 32 + r] = (bfr)(pr & 0xffffu);
;         Cs[(row + 1) * CSS + wn * 128 + nt * 32 + r] = (bfr)(pr >> 16);
;       }
;   __syncthreads();
	ds_read_b128 v[170:173], v142
	s_waitcnt lgkmcnt(0)
	v_mfma_f32_32x32x16_bf16 v[66:81], v[130:133], v[134:137], v[66:81]
	ds_read_b128 v[130:133], v169
	v_mfma_f32_32x32x16_bf16 v[2:17], v[138:141], v[134:137], v[2:17]
	ds_read_b128 v[134:137], v142 offset:2048
	ds_read_b128 v[142:145], v169 offset:2048
	v_add_u32_e32 v138, s25, v160
	s_waitcnt lgkmcnt(0)
	v_mfma_f32_32x32x16_bf16 v[114:129], v[170:173], v[130:133], v[114:129]
	v_mfma_f32_32x32x16_bf16 v[50:65], v[134:137], v[130:133], v[50:65]
	ds_read_b128 v[130:133], v138 offset:6144
	ds_read_b128 v[146:149], v138 offset:4096
	ds_read_b128 v[174:177], v138 offset:2048
	ds_read_b128 v[178:181], v138
	ds_read_b128 v[138:141], v182 offset:2048
	ds_read_b128 v[182:185], v182
	v_mfma_f32_32x32x16_bf16 v[98:113], v[170:173], v[142:145], v[98:113]
	v_mfma_f32_32x32x16_bf16 v[34:49], v[134:137], v[142:145], v[34:49]
	ds_read_b128 v[142:145], v169 offset:6144
	ds_read_b128 v[186:189], v169 offset:4096
	s_waitcnt vmcnt(0)
	v_add_u32_e32 v169, s40, v159
	s_waitcnt lgkmcnt(0)
	s_barrier
	ds_read_b128 v[190:193], v169
	ds_read_b128 v[194:197], v234
	s_waitcnt lgkmcnt(0)
	v_mfma_f32_32x32x16_bf16 v[114:129], v[182:185], v[178:181], v[114:129]
	ds_read_b128 v[198:201], v202 offset:2048
	ds_read_b128 v[202:205], v202
	ds_read_b128 v[206:209], v226 offset:2048
	ds_read_b128 v[210:213], v226
	ds_read_b128 v[214:217], v234 offset:2048
	ds_read_b128 v[218:221], v169 offset:2048
	ds_read_b128 v[222:225], v226 offset:6144
	ds_read_b128 v[226:229], v226 offset:4096
	ds_read_b128 v[230:233], v234 offset:6144
	ds_read_b128 v[234:237], v234 offset:4096
	v_lshl_or_b32 v169, s16, 6, v161
	s_waitcnt lgkmcnt(0)
	s_barrier
	v_mfma_f32_32x32x16_bf16 v[82:97], v[170:173], v[186:189], v[82:97]
	v_mfma_f32_32x32x16_bf16 v[114:129], v[190:193], v[194:197], v[114:129]
	v_mfma_f32_32x32x16_bf16 v[98:113], v[182:185], v[174:177], v[98:113]
	v_mfma_f32_32x32x16_bf16 v[66:81], v[170:173], v[142:145], v[66:81]
	v_mfma_f32_32x32x16_bf16 v[82:97], v[182:185], v[146:149], v[82:97]
	s_waitcnt lgkmcnt(0)
	v_mfma_f32_32x32x16_bf16 v[114:129], v[202:205], v[210:213], v[114:129]
	v_mfma_f32_32x32x16_bf16 v[98:113], v[190:193], v[214:217], v[98:113]
	s_nop 10
	v_cvt_pk_bf16_f32 v238, v114, v115
	v_lshl_or_b32 v114, s26, 8, v165
	v_mad_u64_u32 v[114:115], s[24:25], v169, s35, v[114:115]
	v_cvt_pk_bf16_f32 v115, v116, v117
	ds_write_b16 v114, v238
	ds_write_b16_d16_hi v114, v238 offset:528
	ds_write_b16 v114, v115 offset:1056
	ds_write_b16_d16_hi v114, v115 offset:1584
	v_mfma_f32_32x32x16_bf16 v[66:81], v[182:185], v[130:133], v[66:81]
	v_cvt_pk_bf16_f32 v115, v118, v119
	ds_write_b16 v114, v115 offset:4224
	ds_write_b16_d16_hi v114, v115 offset:4752
	v_cvt_pk_bf16_f32 v115, v120, v121
	ds_write_b16 v114, v115 offset:5280
	ds_write_b16_d16_hi v114, v115 offset:5808
	v_cvt_pk_bf16_f32 v115, v122, v123
	ds_write_b16 v114, v115 offset:8448
	ds_write_b16_d16_hi v114, v115 offset:8976
	v_mfma_f32_32x32x16_bf16 v[82:97], v[190:193], v[234:237], v[82:97]
	v_cvt_pk_bf16_f32 v115, v124, v125
	ds_write_b16 v114, v115 offset:9504
	ds_write_b16_d16_hi v114, v115 offset:10032
	v_cvt_pk_bf16_f32 v115, v126, v127
	ds_write_b16 v114, v115 offset:12672
	ds_write_b16_d16_hi v114, v115 offset:13200
	v_cvt_pk_bf16_f32 v115, v128, v129
	ds_write_b16 v114, v115 offset:13728
	ds_write_b16_d16_hi v114, v115 offset:14256
	v_mfma_f32_32x32x16_bf16 v[98:113], v[202:205], v[206:209], v[98:113]
	v_mfma_f32_32x32x16_bf16 v[50:65], v[138:141], v[178:181], v[50:65]
	s_nop 10
	v_cvt_pk_bf16_f32 v98, v98, v99
	ds_write_b16 v114, v98 offset:64
	ds_write_b16_d16_hi v114, v98 offset:592
	v_cvt_pk_bf16_f32 v98, v100, v101
	ds_write_b16 v114, v98 offset:1120
	ds_write_b16_d16_hi v114, v98 offset:1648
	v_cvt_pk_bf16_f32 v98, v102, v103
	ds_write_b16 v114, v98 offset:4288
	ds_write_b16_d16_hi v114, v98 offset:4816
	v_cvt_pk_bf16_f32 v98, v104, v105
	v_mfma_f32_32x32x16_bf16 v[66:81], v[190:193], v[230:233], v[66:81]
	ds_write_b16 v114, v98 offset:5344
	ds_write_b16_d16_hi v114, v98 offset:5872
	v_cvt_pk_bf16_f32 v98, v106, v107
	ds_write_b16 v114, v98 offset:8512
	ds_write_b16_d16_hi v114, v98 offset:9040
	v_cvt_pk_bf16_f32 v98, v108, v109
	ds_write_b16 v114, v98 offset:9568
	ds_write_b16_d16_hi v114, v98 offset:10096
	v_cvt_pk_bf16_f32 v98, v110, v111
	v_mfma_f32_32x32x16_bf16 v[82:97], v[202:205], v[226:229], v[82:97]
	ds_write_b16 v114, v98 offset:12736
	ds_write_b16_d16_hi v114, v98 offset:13264
	v_cvt_pk_bf16_f32 v98, v112, v113
	ds_write_b16 v114, v98 offset:13792
	ds_write_b16_d16_hi v114, v98 offset:14320
	s_nop 6
	v_cvt_pk_bf16_f32 v82, v82, v83
	v_mfma_f32_32x32x16_bf16 v[18:33], v[134:137], v[186:189], v[18:33]
	ds_write_b16 v114, v82 offset:128
	ds_write_b16_d16_hi v114, v82 offset:656
	v_cvt_pk_bf16_f32 v82, v84, v85
	ds_write_b16 v114, v82 offset:1184
	ds_write_b16_d16_hi v114, v82 offset:1712
	v_cvt_pk_bf16_f32 v82, v86, v87
	ds_write_b16 v114, v82 offset:4352
	ds_write_b16_d16_hi v114, v82 offset:4880
	v_cvt_pk_bf16_f32 v82, v88, v89
	v_mfma_f32_32x32x16_bf16 v[34:49], v[138:141], v[174:177], v[34:49]
	ds_write_b16 v114, v82 offset:5408
	ds_write_b16_d16_hi v114, v82 offset:5936
	v_cvt_pk_bf16_f32 v82, v90, v91
	ds_write_b16 v114, v82 offset:8576
	ds_write_b16_d16_hi v114, v82 offset:9104
	v_cvt_pk_bf16_f32 v82, v92, v93
	ds_write_b16 v114, v82 offset:9632
	ds_write_b16_d16_hi v114, v82 offset:10160
	v_cvt_pk_bf16_f32 v82, v94, v95
	ds_write_b16 v114, v82 offset:12800
	ds_write_b16_d16_hi v114, v82 offset:13328
	v_mfma_f32_32x32x16_bf16 v[50:65], v[218:221], v[194:197], v[50:65]
	v_cvt_pk_bf16_f32 v82, v96, v97
	ds_write_b16 v114, v82 offset:13856
; DI unsigned pk2(float a, float b) { fl2_t f = {a, b}; bf2_t r = __builtin_convertvector(f, bf2_t); return __builtin_bit_cast(unsigned, r); }
; #define RAW_BARRIER() do { asm volatile("s_waitcnt lgkmcnt(0)" ::: "memory"); __builtin_amdgcn_s_barrier(); } while (0)
; template <typename FA, typename FB, typename FE>
; DI void gemm_tile(char* lds, int K, int astride, int bstride, FA arow, FB brow, FE epi) {
;     ...
;   RAW_BARRIER();
;   bfr* Cs = (bfr*)lds;
; #pragma unroll
;   for (int mt = 0; mt < 2; ++mt)
; #pragma unroll
;     for (int nt = 0; nt < 4; ++nt)
; #pragma unroll
;       for (int i = 0; i < 16; i += 2) {
;         const int row = wm * 64 + mt * 32 + (i & 3) + 8 * (i >> 2) + 4 * h8;
;         const unsigned pr = pk2(acc[mt][nt][i], acc[mt][nt][i + 1]);
;         Cs[row * CSS + wn * 128 + nt * 32 + r] = (bfr)(pr & 0xffffu);
;         Cs[(row + 1) * CSS + wn * 128 + nt * 32 + r] = (bfr)(pr >> 16);
;       }
;   __syncthreads();
; DI void phase_moe(const Params& p, char* lds, int mode) {
;     ...
;         if (r0 + grow < n) {
	ds_write_b16_d16_hi v114, v82 offset:14384
	v_mfma_f32_32x32x16_bf16 v[66:81], v[202:205], v[222:225], v[66:81]
	v_mfma_f32_32x32x16_bf16 v[2:17], v[134:137], v[142:145], v[2:17]
	s_nop 10
	v_cvt_pk_bf16_f32 v66, v66, v67
	ds_write_b16 v114, v66 offset:192
	ds_write_b16_d16_hi v114, v66 offset:720
	v_cvt_pk_bf16_f32 v66, v68, v69
	ds_write_b16 v114, v66 offset:1248
	ds_write_b16_d16_hi v114, v66 offset:1776
	v_cvt_pk_bf16_f32 v66, v70, v71
	ds_write_b16 v114, v66 offset:4416
	ds_write_b16_d16_hi v114, v66 offset:4944
	v_mfma_f32_32x32x16_bf16 v[18:33], v[138:141], v[146:149], v[18:33]
	v_cvt_pk_bf16_f32 v66, v72, v73
	ds_write_b16 v114, v66 offset:5472
	ds_write_b16_d16_hi v114, v66 offset:6000
	v_cvt_pk_bf16_f32 v66, v74, v75
	ds_write_b16 v114, v66 offset:8640
	ds_write_b16_d16_hi v114, v66 offset:9168
	v_cvt_pk_bf16_f32 v66, v76, v77
	ds_write_b16 v114, v66 offset:9696
	ds_write_b16_d16_hi v114, v66 offset:10224
	v_cvt_pk_bf16_f32 v66, v78, v79
	v_mfma_f32_32x32x16_bf16 v[34:49], v[218:221], v[214:217], v[34:49]
	ds_write_b16 v114, v66 offset:12864
	ds_write_b16_d16_hi v114, v66 offset:13392
	v_cvt_pk_bf16_f32 v66, v80, v81
	ds_write_b16 v114, v66 offset:13920
	ds_write_b16_d16_hi v114, v66 offset:14448
	v_mfma_f32_32x32x16_bf16 v[50:65], v[198:201], v[210:213], v[50:65]
	v_mfma_f32_32x32x16_bf16 v[2:17], v[138:141], v[130:133], v[2:17]
	s_nop 10
	v_cvt_pk_bf16_f32 v50, v50, v51
	ds_write_b16 v114, v50 offset:16896
	ds_write_b16_d16_hi v114, v50 offset:17424
	v_cvt_pk_bf16_f32 v50, v52, v53
	ds_write_b16 v114, v50 offset:17952
	ds_write_b16_d16_hi v114, v50 offset:18480
	v_cvt_pk_bf16_f32 v50, v54, v55
	ds_write_b16 v114, v50 offset:21120
	ds_write_b16_d16_hi v114, v50 offset:21648
	v_mfma_f32_32x32x16_bf16 v[18:33], v[218:221], v[234:237], v[18:33]
	v_cvt_pk_bf16_f32 v50, v56, v57
	ds_write_b16 v114, v50 offset:22176
	ds_write_b16_d16_hi v114, v50 offset:22704
	v_cvt_pk_bf16_f32 v50, v58, v59
	ds_write_b16 v114, v50 offset:25344
	ds_write_b16_d16_hi v114, v50 offset:25872
	v_cvt_pk_bf16_f32 v50, v60, v61
	ds_write_b16 v114, v50 offset:26400
	ds_write_b16_d16_hi v114, v50 offset:26928
	v_cvt_pk_bf16_f32 v50, v62, v63
	v_mfma_f32_32x32x16_bf16 v[34:49], v[198:201], v[206:209], v[34:49]
	ds_write_b16 v114, v50 offset:29568
	ds_write_b16_d16_hi v114, v50 offset:30096
	v_cvt_pk_bf16_f32 v50, v64, v65
	ds_write_b16 v114, v50 offset:30624
	ds_write_b16_d16_hi v114, v50 offset:31152
	s_nop 6
	v_cvt_pk_bf16_f32 v34, v34, v35
	v_mfma_f32_32x32x16_bf16 v[2:17], v[218:221], v[230:233], v[2:17]
	ds_write_b16 v114, v34 offset:16960
	ds_write_b16_d16_hi v114, v34 offset:17488
	v_cvt_pk_bf16_f32 v34, v36, v37
	ds_write_b16 v114, v34 offset:18016
	ds_write_b16_d16_hi v114, v34 offset:18544
	v_cvt_pk_bf16_f32 v34, v38, v39
	ds_write_b16 v114, v34 offset:21184
	ds_write_b16_d16_hi v114, v34 offset:21712
	v_cvt_pk_bf16_f32 v34, v40, v41
	ds_write_b16 v114, v34 offset:22240
	ds_write_b16_d16_hi v114, v34 offset:22768
	v_mfma_f32_32x32x16_bf16 v[18:33], v[198:201], v[226:229], v[18:33]
	v_cvt_pk_bf16_f32 v34, v42, v43
	ds_write_b16 v114, v34 offset:25408
	ds_write_b16_d16_hi v114, v34 offset:25936
	v_cvt_pk_bf16_f32 v34, v44, v45
	ds_write_b16 v114, v34 offset:26464
	ds_write_b16_d16_hi v114, v34 offset:26992
	v_cvt_pk_bf16_f32 v34, v46, v47
	ds_write_b16 v114, v34 offset:29632
	ds_write_b16_d16_hi v114, v34 offset:30160
	v_mfma_f32_32x32x16_bf16 v[2:17], v[198:201], v[222:225], v[2:17]
	v_cvt_pk_bf16_f32 v34, v48, v49
	s_nop 0
	v_cvt_pk_bf16_f32 v18, v18, v19
	ds_write_b16 v114, v34 offset:30688
	ds_write_b16_d16_hi v114, v34 offset:31216
	ds_write_b16 v114, v18 offset:17024
	ds_write_b16_d16_hi v114, v18 offset:17552
	v_cvt_pk_bf16_f32 v18, v20, v21
	ds_write_b16 v114, v18 offset:18080
	ds_write_b16_d16_hi v114, v18 offset:18608
	v_cvt_pk_bf16_f32 v18, v22, v23
	ds_write_b16 v114, v18 offset:21248
	ds_write_b16_d16_hi v114, v18 offset:21776
	v_cvt_pk_bf16_f32 v18, v24, v25
	ds_write_b16 v114, v18 offset:22304
	ds_write_b16_d16_hi v114, v18 offset:22832
	v_cvt_pk_bf16_f32 v18, v26, v27
	ds_write_b16 v114, v18 offset:25472
	ds_write_b16_d16_hi v114, v18 offset:26000
	v_cvt_pk_bf16_f32 v18, v28, v29
	ds_write_b16 v114, v18 offset:26528
	ds_write_b16_d16_hi v114, v18 offset:27056
	v_cvt_pk_bf16_f32 v18, v30, v31
	ds_write_b16 v114, v18 offset:29696
	ds_write_b16_d16_hi v114, v18 offset:30224
	v_cvt_pk_bf16_f32 v18, v32, v33
	v_cvt_pk_bf16_f32 v2, v2, v3
	ds_write_b16 v114, v18 offset:30752
	ds_write_b16_d16_hi v114, v18 offset:31280
	ds_write_b16 v114, v2 offset:17088
	ds_write_b16_d16_hi v114, v2 offset:17616
	v_cvt_pk_bf16_f32 v2, v4, v5
	ds_write_b16 v114, v2 offset:18144
	ds_write_b16_d16_hi v114, v2 offset:18672
	v_cvt_pk_bf16_f32 v2, v6, v7
	ds_write_b16 v114, v2 offset:21312
	ds_write_b16_d16_hi v114, v2 offset:21840
	v_cvt_pk_bf16_f32 v2, v8, v9
	ds_write_b16 v114, v2 offset:22368
	ds_write_b16_d16_hi v114, v2 offset:22896
	v_cvt_pk_bf16_f32 v2, v10, v11
	ds_write_b16 v114, v2 offset:25536
	ds_write_b16_d16_hi v114, v2 offset:26064
	v_cvt_pk_bf16_f32 v2, v12, v13
	ds_write_b16 v114, v2 offset:26592
	ds_write_b16_d16_hi v114, v2 offset:27120
	v_cvt_pk_bf16_f32 v2, v14, v15
	ds_write_b16 v114, v2 offset:29760
	ds_write_b16_d16_hi v114, v2 offset:30288
	v_cvt_pk_bf16_f32 v2, v16, v17
	ds_write_b16 v114, v2 offset:30816
	ds_write_b16_d16_hi v114, v2 offset:31344
	v_add_u32_e32 v2, v162, v168
	s_waitcnt vmcnt(0)
	v_cmp_lt_i32_e32 vcc, v2, v167
	s_waitcnt lgkmcnt(0)
	s_barrier
	s_and_saveexec_b64 s[24:25], vcc
	s_cbranch_execz .LBB0_289
; DI unsigned pk2(float a, float b) { fl2_t f = {a, b}; bf2_t r = __builtin_convertvector(f, bf2_t); return __builtin_bit_cast(unsigned, r); }
; DI void phase_moe(const Params& p, char* lds, int mode) {
;     ...
;         const int row = tid & 127, hf = tid >> 7, grow = half * 128 + row;
;         if (r0 + grow < n) {
;           bfr* dst = act + ((size_t)(nt * 2 + hf) * (2 * T) + (lb[li] + r0 + grow)) * 32;
; #pragma unroll
;           for (int q = 0; q < 4; ++q) {
;             float z[8];
; #pragma unroll
;             for (int u = 0; u < 2; ++u) {
;               float4 g = cs4(Cs, row, hf * 32 + q * 8 + u * 4);
;               float4 up = cs4(Cs, row, 64 + hf * 32 + q * 8 + u * 4);
;               z[u * 4 + 0] = g.x / (1.f + __expf(-g.x)) * up.x; z[u * 4 + 1] = g.y / (1.f + __expf(-g.y)) * up.y;
;               z[u * 4 + 2] = g.z / (1.f + __expf(-g.z)) * up.z; z[u * 4 + 3] = g.w / (1.f + __expf(-g.w)) * up.w;
;             }
;             u32x4 o; o[0] = pk2(z[0], z[1]); o[1] = pk2(z[2], z[3]); o[2] = pk2(z[4], z[5]); o[3] = pk2(z[6], z[7]);
;             *(u32x4*)(dst + q * 8) = o;
;           }
	s_add_i32 s16, s39, 0x25e00
	v_mov_b32_e32 v3, s16
	ds_read_b32 v3, v3
	ds_read_b128 v[18:21], v164
	ds_read_b128 v[10:13], v164 offset:16
	v_lshl_or_b32 v30, s37, 2, v163
	s_waitcnt lgkmcnt(1)
	v_lshlrev_b32_e32 v31, 16, v18
	v_add_u32_e32 v26, v3, v2
	v_ashrrev_i32_e32 v27, 31, v26
	v_mad_i64_i32 v[2:3], s[26:27], v30, s36, v[26:27]
	v_lshlrev_b64 v[2:3], 6, v[2:3]
	v_lshl_add_u64 v[28:29], s[10:11], 0, v[2:3]
	v_and_b32_e32 v18, 0xffff0000, v18
	v_mul_f32_e32 v2, 0xbfb8aa3b, v31
	v_exp_f32_e32 v14, v2
	v_mul_f32_e32 v2, 0xbfb8aa3b, v18
	v_exp_f32_e32 v15, v2
	ds_read_b128 v[6:9], v164 offset:32
	ds_read_b128 v[2:5], v164 offset:48
	ds_read_b128 v[22:25], v164 offset:128
	v_pk_add_f32 v[32:33], v[14:15], 1.0 op_sel_hi:[1,0]
	s_nop 0
	s_waitcnt lgkmcnt(0)
	v_lshlrev_b32_e32 v34, 16, v22
	v_and_b32_e32 v35, 0xffff0000, v22
	ds_read_b128 v[14:17], v164 offset:144
	v_rcp_f32_e32 v22, v33
	s_nop 0
	v_mul_f32_e32 v33, v18, v22
	v_and_b32_e32 v38, 0xffff0000, v19
	v_lshlrev_b32_e32 v37, 16, v19
	v_mul_f32_e32 v18, 0xbfb8aa3b, v37
	v_mul_f32_e32 v19, 0xbfb8aa3b, v38
	v_exp_f32_e32 v18, v18
	v_exp_f32_e32 v19, v19
	v_rcp_f32_e32 v22, v32
	s_nop 0
	v_mul_f32_e32 v32, v31, v22
	v_pk_mul_f32 v[32:33], v[32:33], v[34:35]
	v_pk_add_f32 v[18:19], v[18:19], 1.0 op_sel_hi:[1,0]
	v_lshlrev_b32_e32 v22, 16, v23
	v_and_b32_e32 v23, 0xffff0000, v23
	v_rcp_f32_e32 v31, v19
	s_nop 0
	v_mul_f32_e32 v19, v38, v31
	v_lshlrev_b32_e32 v38, 16, v20
	v_and_b32_e32 v20, 0xffff0000, v20
	v_mul_f32_e32 v34, 0xbfb8aa3b, v38
	v_mul_f32_e32 v35, 0xbfb8aa3b, v20
	v_exp_f32_e32 v34, v34
	v_exp_f32_e32 v35, v35
	v_rcp_f32_e32 v31, v18
	s_nop 0
	v_mul_f32_e32 v18, v37, v31
	v_pk_mul_f32 v[22:23], v[18:19], v[22:23]
	v_pk_add_f32 v[34:35], v[34:35], 1.0 op_sel_hi:[1,0]
	v_lshlrev_b32_e32 v18, 16, v24
	v_and_b32_e32 v19, 0xffff0000, v24
	v_rcp_f32_e32 v24, v35
	s_nop 0
	v_mul_f32_e32 v35, v20, v24
	v_and_b32_e32 v37, 0xffff0000, v21
	v_lshlrev_b32_e32 v36, 16, v21
	v_mul_f32_e32 v20, 0xbfb8aa3b, v36
	v_mul_f32_e32 v21, 0xbfb8aa3b, v37
	v_exp_f32_e32 v20, v20
	v_exp_f32_e32 v21, v21
	v_rcp_f32_e32 v24, v34
	s_nop 0
	v_mul_f32_e32 v34, v38, v24
	v_pk_mul_f32 v[34:35], v[34:35], v[18:19]
	v_pk_add_f32 v[20:21], v[20:21], 1.0 op_sel_hi:[1,0]
	v_lshlrev_b32_e32 v18, 16, v25
	v_and_b32_e32 v19, 0xffff0000, v25
	v_rcp_f32_e32 v24, v21
	s_nop 0
	v_mul_f32_e32 v21, v37, v24
	v_rcp_f32_e32 v24, v20
	s_nop 0
	v_mul_f32_e32 v20, v36, v24
	v_lshlrev_b32_e32 v31, 16, v10
	v_pk_mul_f32 v[24:25], v[20:21], v[18:19]
	v_and_b32_e32 v10, 0xffff0000, v10
	v_mul_f32_e32 v19, 0xbfb8aa3b, v31
	v_cvt_pk_bf16_f32 v18, v32, v33
	v_exp_f32_e32 v32, v19
	v_mul_f32_e32 v19, 0xbfb8aa3b, v10
	v_exp_f32_e32 v33, v19
	v_cvt_pk_bf16_f32 v19, v22, v23
	v_cvt_pk_bf16_f32 v21, v24, v25
	v_cvt_pk_bf16_f32 v20, v34, v35
	v_pk_add_f32 v[22:23], v[32:33], 1.0 op_sel_hi:[1,0]
	global_store_dwordx4 v[28:29], v[18:21], off
	s_nop 1
	s_waitcnt lgkmcnt(0)
	v_lshlrev_b32_e32 v18, 16, v14
	v_and_b32_e32 v19, 0xffff0000, v14
	v_rcp_f32_e32 v14, v23
	s_nop 0
	v_mul_f32_e32 v21, v10, v14
	v_lshlrev_b32_e32 v23, 16, v11
	v_and_b32_e32 v24, 0xffff0000, v11
	v_mul_f32_e32 v10, 0xbfb8aa3b, v23
	v_mul_f32_e32 v11, 0xbfb8aa3b, v24
	v_exp_f32_e32 v10, v10
	v_exp_f32_e32 v11, v11
	v_rcp_f32_e32 v14, v22
	s_nop 0
	v_mul_f32_e32 v20, v31, v14
	v_pk_mul_f32 v[18:19], v[20:21], v[18:19]
	v_pk_add_f32 v[10:11], v[10:11], 1.0 op_sel_hi:[1,0]
	v_lshlrev_b32_e32 v14, 16, v15
	v_and_b32_e32 v15, 0xffff0000, v15
	v_rcp_f32_e32 v20, v11
	s_nop 0
	v_mul_f32_e32 v11, v24, v20
	v_lshlrev_b32_e32 v25, 16, v12
	v_and_b32_e32 v12, 0xffff0000, v12
	v_mul_f32_e32 v20, 0xbfb8aa3b, v25
	v_mul_f32_e32 v21, 0xbfb8aa3b, v12
	v_exp_f32_e32 v20, v20
	v_exp_f32_e32 v21, v21
	v_rcp_f32_e32 v22, v10
	s_nop 0
	v_mul_f32_e32 v10, v23, v22
	v_pk_mul_f32 v[14:15], v[10:11], v[14:15]
	v_pk_add_f32 v[20:21], v[20:21], 1.0 op_sel_hi:[1,0]
	v_lshlrev_b32_e32 v10, 16, v16
	v_and_b32_e32 v11, 0xffff0000, v16
	v_rcp_f32_e32 v16, v21
	s_nop 0
	v_mul_f32_e32 v21, v12, v16
	v_and_b32_e32 v24, 0xffff0000, v13
	v_lshlrev_b32_e32 v23, 16, v13
	v_mul_f32_e32 v12, 0xbfb8aa3b, v23
	v_mul_f32_e32 v13, 0xbfb8aa3b, v24
	v_exp_f32_e32 v12, v12
	v_exp_f32_e32 v13, v13
	v_rcp_f32_e32 v16, v20
	s_nop 0
	v_mul_f32_e32 v20, v25, v16
	v_pk_mul_f32 v[20:21], v[20:21], v[10:11]
	v_pk_add_f32 v[12:13], v[12:13], 1.0 op_sel_hi:[1,0]
	v_lshlrev_b32_e32 v10, 16, v17
	v_and_b32_e32 v11, 0xffff0000, v17
	v_rcp_f32_e32 v16, v13
	s_nop 0
	v_mul_f32_e32 v13, v24, v16
	v_rcp_f32_e32 v16, v12
	s_nop 0
	v_mul_f32_e32 v12, v23, v16
	v_lshlrev_b32_e32 v22, 16, v6
	v_pk_mul_f32 v[16:17], v[12:13], v[10:11]
	v_and_b32_e32 v6, 0xffff0000, v6
	v_mul_f32_e32 v13, 0xbfb8aa3b, v22
	v_cvt_pk_bf16_f32 v10, v18, v19
	v_exp_f32_e32 v18, v13
	v_mul_f32_e32 v13, 0xbfb8aa3b, v6
	v_exp_f32_e32 v19, v13
	v_cvt_pk_bf16_f32 v11, v14, v15
	v_cvt_pk_bf16_f32 v13, v16, v17
	ds_read_b128 v[14:17], v164 offset:160
	v_pk_add_f32 v[18:19], v[18:19], 1.0 op_sel_hi:[1,0]
	v_cvt_pk_bf16_f32 v12, v20, v21
	s_waitcnt lgkmcnt(0)
; DI unsigned pk2(float a, float b) { fl2_t f = {a, b}; bf2_t r = __builtin_convertvector(f, bf2_t); return __builtin_bit_cast(unsigned, r); }
; DI void phase_moe(const Params& p, char* lds, int mode) {
;     ...
; #pragma unroll
;           for (int q = 0; q < 4; ++q) {
;             float z[8];
; #pragma unroll
;             for (int u = 0; u < 2; ++u) {
;               float4 g = cs4(Cs, row, hf * 32 + q * 8 + u * 4);
;               float4 up = cs4(Cs, row, 64 + hf * 32 + q * 8 + u * 4);
;               z[u * 4 + 0] = g.x / (1.f + __expf(-g.x)) * up.x; z[u * 4 + 1] = g.y / (1.f + __expf(-g.y)) * up.y;
;               z[u * 4 + 2] = g.z / (1.f + __expf(-g.z)) * up.z; z[u * 4 + 3] = g.w / (1.f + __expf(-g.w)) * up.w;
;             }
;             u32x4 o; o[0] = pk2(z[0], z[1]); o[1] = pk2(z[2], z[3]); o[2] = pk2(z[4], z[5]); o[3] = pk2(z[6], z[7]);
;             *(u32x4*)(dst + q * 8) = o;
;           }
	v_lshlrev_b32_e32 v20, 16, v14
	v_and_b32_e32 v21, 0xffff0000, v14
	global_store_dwordx4 v[28:29], v[10:13], off offset:16
	v_rcp_f32_e32 v14, v19
	s_nop 0
	v_mul_f32_e32 v19, v6, v14
	v_and_b32_e32 v25, 0xffff0000, v7
	v_lshlrev_b32_e32 v24, 16, v7
	v_mul_f32_e32 v6, 0xbfb8aa3b, v24
	v_mul_f32_e32 v7, 0xbfb8aa3b, v25
	v_exp_f32_e32 v6, v6
	v_exp_f32_e32 v7, v7
	v_rcp_f32_e32 v14, v18
	s_nop 0
	v_mul_f32_e32 v18, v22, v14
	v_pk_mul_f32 v[18:19], v[18:19], v[20:21]
	v_pk_add_f32 v[6:7], v[6:7], 1.0 op_sel_hi:[1,0]
	v_lshlrev_b32_e32 v14, 16, v15
	v_and_b32_e32 v15, 0xffff0000, v15
	ds_read_b128 v[10:13], v164 offset:176
	v_rcp_f32_e32 v20, v7
	s_nop 0
	v_mul_f32_e32 v7, v25, v20
	v_lshlrev_b32_e32 v25, 16, v8
	v_and_b32_e32 v8, 0xffff0000, v8
	v_mul_f32_e32 v20, 0xbfb8aa3b, v25
	v_mul_f32_e32 v21, 0xbfb8aa3b, v8
	v_exp_f32_e32 v20, v20
	v_exp_f32_e32 v21, v21
	v_rcp_f32_e32 v22, v6
	s_nop 0
	v_mul_f32_e32 v6, v24, v22
	v_pk_mul_f32 v[14:15], v[6:7], v[14:15]
	v_pk_add_f32 v[20:21], v[20:21], 1.0 op_sel_hi:[1,0]
	v_lshlrev_b32_e32 v6, 16, v16
	v_and_b32_e32 v7, 0xffff0000, v16
	v_rcp_f32_e32 v16, v21
	s_nop 0
	v_mul_f32_e32 v21, v8, v16
	v_and_b32_e32 v24, 0xffff0000, v9
	v_lshlrev_b32_e32 v23, 16, v9
	v_mul_f32_e32 v8, 0xbfb8aa3b, v23
	v_mul_f32_e32 v9, 0xbfb8aa3b, v24
	v_exp_f32_e32 v8, v8
	v_exp_f32_e32 v9, v9
	v_rcp_f32_e32 v16, v20
	s_nop 0
	v_mul_f32_e32 v20, v25, v16
	v_pk_mul_f32 v[20:21], v[20:21], v[6:7]
	v_pk_add_f32 v[8:9], v[8:9], 1.0 op_sel_hi:[1,0]
	v_lshlrev_b32_e32 v6, 16, v17
	v_and_b32_e32 v7, 0xffff0000, v17
	v_rcp_f32_e32 v16, v9
	s_nop 0
	v_mul_f32_e32 v9, v24, v16
	v_rcp_f32_e32 v16, v8
	s_nop 0
	v_mul_f32_e32 v8, v23, v16
	v_lshlrev_b32_e32 v22, 16, v2
	v_pk_mul_f32 v[16:17], v[8:9], v[6:7]
	v_and_b32_e32 v2, 0xffff0000, v2
	v_mul_f32_e32 v7, 0xbfb8aa3b, v22
	v_cvt_pk_bf16_f32 v6, v18, v19
	v_exp_f32_e32 v18, v7
	v_mul_f32_e32 v7, 0xbfb8aa3b, v2
	v_exp_f32_e32 v19, v7
	v_cvt_pk_bf16_f32 v7, v14, v15
	v_cvt_pk_bf16_f32 v9, v16, v17
	v_cvt_pk_bf16_f32 v8, v20, v21
	v_pk_add_f32 v[14:15], v[18:19], 1.0 op_sel_hi:[1,0]
	global_store_dwordx4 v[28:29], v[6:9], off offset:32
	s_nop 1
	s_waitcnt lgkmcnt(0)
	v_lshlrev_b32_e32 v6, 16, v10
	v_and_b32_e32 v7, 0xffff0000, v10
	v_rcp_f32_e32 v8, v15
	s_nop 0
	v_mul_f32_e32 v9, v2, v8
	v_and_b32_e32 v17, 0xffff0000, v3
	v_lshlrev_b32_e32 v15, 16, v3
	v_mul_f32_e32 v2, 0xbfb8aa3b, v15
	v_mul_f32_e32 v3, 0xbfb8aa3b, v17
	v_exp_f32_e32 v2, v2
	v_exp_f32_e32 v3, v3
	v_rcp_f32_e32 v8, v14
	s_nop 0
	v_mul_f32_e32 v8, v22, v8
	v_pk_mul_f32 v[6:7], v[8:9], v[6:7]
	v_pk_add_f32 v[2:3], v[2:3], 1.0 op_sel_hi:[1,0]
	v_lshlrev_b32_e32 v8, 16, v11
	v_and_b32_e32 v9, 0xffff0000, v11
	v_rcp_f32_e32 v10, v3
	s_nop 0
	v_mul_f32_e32 v3, v17, v10
	v_lshlrev_b32_e32 v17, 16, v4
	v_and_b32_e32 v4, 0xffff0000, v4
	v_mul_f32_e32 v10, 0xbfb8aa3b, v17
	v_mul_f32_e32 v11, 0xbfb8aa3b, v4
	v_exp_f32_e32 v10, v10
	v_exp_f32_e32 v11, v11
	v_rcp_f32_e32 v14, v2
	s_nop 0
	v_mul_f32_e32 v2, v15, v14
	v_pk_mul_f32 v[8:9], v[2:3], v[8:9]
	v_pk_add_f32 v[10:11], v[10:11], 1.0 op_sel_hi:[1,0]
	v_lshlrev_b32_e32 v2, 16, v12
	v_and_b32_e32 v3, 0xffff0000, v12
	v_rcp_f32_e32 v12, v11
	s_nop 0
	v_mul_f32_e32 v11, v4, v12
	v_and_b32_e32 v16, 0xffff0000, v5
	v_lshlrev_b32_e32 v15, 16, v5
	v_mul_f32_e32 v4, 0xbfb8aa3b, v15
	v_mul_f32_e32 v5, 0xbfb8aa3b, v16
	v_exp_f32_e32 v4, v4
	v_exp_f32_e32 v5, v5
	v_rcp_f32_e32 v12, v10
	s_nop 0
	v_mul_f32_e32 v10, v17, v12
	v_pk_mul_f32 v[10:11], v[10:11], v[2:3]
	v_pk_add_f32 v[4:5], v[4:5], 1.0 op_sel_hi:[1,0]
	v_lshlrev_b32_e32 v2, 16, v13
	v_and_b32_e32 v3, 0xffff0000, v13
	v_rcp_f32_e32 v12, v5
	s_nop 0
	v_mul_f32_e32 v5, v16, v12
	v_rcp_f32_e32 v12, v4
	s_nop 0
	v_mul_f32_e32 v4, v15, v12
	v_pk_mul_f32 v[12:13], v[4:5], v[2:3]
	v_cvt_pk_bf16_f32 v4, v10, v11
	v_cvt_pk_bf16_f32 v5, v12, v13
	ds_read_b128 v[10:13], v164 offset:256
	v_cvt_pk_bf16_f32 v2, v6, v7
	v_cvt_pk_bf16_f32 v3, v8, v9
	global_store_dwordx4 v[28:29], v[2:5], off offset:48
	ds_read_b128 v[16:19], v164 offset:384
	s_waitcnt lgkmcnt(1)
	v_lshlrev_b32_e32 v24, 16, v10
	v_and_b32_e32 v10, 0xffff0000, v10
	v_mul_f32_e32 v4, 0xbfb8aa3b, v24
	v_mul_f32_e32 v5, 0xbfb8aa3b, v10
	v_exp_f32_e32 v4, v4
	v_exp_f32_e32 v5, v5
	v_or_b32_e32 v2, 2, v30
	v_mad_i64_i32 v[2:3], s[26:27], v2, s36, v[26:27]
	v_pk_add_f32 v[20:21], v[4:5], 1.0 op_sel_hi:[1,0]
	s_waitcnt lgkmcnt(0)
	v_lshlrev_b32_e32 v22, 16, v16
	v_and_b32_e32 v23, 0xffff0000, v16
	ds_read_b128 v[6:9], v164 offset:272
	v_lshlrev_b64 v[2:3], 6, v[2:3]
	v_rcp_f32_e32 v16, v21
	s_nop 0
	v_mul_f32_e32 v21, v10, v16
	v_and_b32_e32 v27, 0xffff0000, v11
	v_lshlrev_b32_e32 v26, 16, v11
	v_mul_f32_e32 v10, 0xbfb8aa3b, v26
	v_mul_f32_e32 v11, 0xbfb8aa3b, v27
	v_exp_f32_e32 v10, v10
	v_exp_f32_e32 v11, v11
	v_rcp_f32_e32 v16, v20
	s_nop 0
	v_mul_f32_e32 v20, v24, v16
	v_pk_mul_f32 v[20:21], v[20:21], v[22:23]
	v_pk_add_f32 v[10:11], v[10:11], 1.0 op_sel_hi:[1,0]
	v_lshlrev_b32_e32 v16, 16, v17
	v_and_b32_e32 v17, 0xffff0000, v17
	v_lshl_add_u64 v[14:15], s[10:11], 0, v[2:3]
	ds_read_b128 v[2:5], v164 offset:400
	v_rcp_f32_e32 v22, v11
	s_nop 0
	v_mul_f32_e32 v11, v27, v22
	v_lshlrev_b32_e32 v27, 16, v12
	v_and_b32_e32 v12, 0xffff0000, v12
	v_mul_f32_e32 v22, 0xbfb8aa3b, v27
	v_mul_f32_e32 v23, 0xbfb8aa3b, v12
	v_exp_f32_e32 v22, v22
	v_exp_f32_e32 v23, v23
	v_rcp_f32_e32 v24, v10
	s_nop 0
	v_mul_f32_e32 v10, v26, v24
	v_pk_mul_f32 v[16:17], v[10:11], v[16:17]
	v_pk_add_f32 v[22:23], v[22:23], 1.0 op_sel_hi:[1,0]
	v_lshlrev_b32_e32 v10, 16, v18
	v_and_b32_e32 v11, 0xffff0000, v18
	v_rcp_f32_e32 v18, v23
	s_nop 0
	v_mul_f32_e32 v23, v12, v18
	v_and_b32_e32 v26, 0xffff0000, v13
	v_lshlrev_b32_e32 v25, 16, v13
	v_mul_f32_e32 v12, 0xbfb8aa3b, v25
	v_mul_f32_e32 v13, 0xbfb8aa3b, v26
	v_exp_f32_e32 v12, v12
	v_exp_f32_e32 v13, v13
	v_rcp_f32_e32 v18, v22
	s_nop 0
	v_mul_f32_e32 v22, v27, v18
	v_pk_mul_f32 v[22:23], v[22:23], v[10:11]
	v_pk_add_f32 v[12:13], v[12:13], 1.0 op_sel_hi:[1,0]
	v_lshlrev_b32_e32 v10, 16, v19
	v_and_b32_e32 v11, 0xffff0000, v19
	v_rcp_f32_e32 v18, v13
	s_nop 0
	v_mul_f32_e32 v13, v26, v18
	v_rcp_f32_e32 v18, v12
	s_nop 0
	v_mul_f32_e32 v12, v25, v18
	s_waitcnt lgkmcnt(1)
; DI unsigned pk2(float a, float b) { fl2_t f = {a, b}; bf2_t r = __builtin_convertvector(f, bf2_t); return __builtin_bit_cast(unsigned, r); }
; DI void phase_moe(const Params& p, char* lds, int mode) {
;     ...
; #pragma unroll
;           for (int q = 0; q < 4; ++q) {
;             float z[8];
; #pragma unroll
;             for (int u = 0; u < 2; ++u) {
;               float4 g = cs4(Cs, row, hf * 32 + q * 8 + u * 4);
;               float4 up = cs4(Cs, row, 64 + hf * 32 + q * 8 + u * 4);
;               z[u * 4 + 0] = g.x / (1.f + __expf(-g.x)) * up.x; z[u * 4 + 1] = g.y / (1.f + __expf(-g.y)) * up.y;
;               z[u * 4 + 2] = g.z / (1.f + __expf(-g.z)) * up.z; z[u * 4 + 3] = g.w / (1.f + __expf(-g.w)) * up.w;
;             }
;             u32x4 o; o[0] = pk2(z[0], z[1]); o[1] = pk2(z[2], z[3]); o[2] = pk2(z[4], z[5]); o[3] = pk2(z[6], z[7]);
;             *(u32x4*)(dst + q * 8) = o;
;           }
	v_lshlrev_b32_e32 v24, 16, v6
	v_pk_mul_f32 v[18:19], v[12:13], v[10:11]
	v_and_b32_e32 v6, 0xffff0000, v6
	v_mul_f32_e32 v11, 0xbfb8aa3b, v24
	v_cvt_pk_bf16_f32 v10, v20, v21
	v_exp_f32_e32 v20, v11
	v_mul_f32_e32 v11, 0xbfb8aa3b, v6
	v_exp_f32_e32 v21, v11
	v_cvt_pk_bf16_f32 v11, v16, v17
	v_cvt_pk_bf16_f32 v13, v18, v19
	v_cvt_pk_bf16_f32 v12, v22, v23
	v_pk_add_f32 v[16:17], v[20:21], 1.0 op_sel_hi:[1,0]
	global_store_dwordx4 v[14:15], v[10:13], off
	s_nop 1
	s_waitcnt lgkmcnt(0)
	v_lshlrev_b32_e32 v10, 16, v2
	v_and_b32_e32 v11, 0xffff0000, v2
	v_rcp_f32_e32 v2, v17
	s_nop 0
	v_mul_f32_e32 v13, v6, v2
	v_and_b32_e32 v19, 0xffff0000, v7
	v_lshlrev_b32_e32 v18, 16, v7
	v_mul_f32_e32 v6, 0xbfb8aa3b, v18
	v_mul_f32_e32 v7, 0xbfb8aa3b, v19
	v_exp_f32_e32 v6, v6
	v_exp_f32_e32 v7, v7
	v_rcp_f32_e32 v2, v16
	s_nop 0
	v_mul_f32_e32 v12, v24, v2
	v_pk_mul_f32 v[16:17], v[12:13], v[10:11]
	v_pk_add_f32 v[6:7], v[6:7], 1.0 op_sel_hi:[1,0]
	v_lshlrev_b32_e32 v2, 16, v3
	v_and_b32_e32 v3, 0xffff0000, v3
	v_rcp_f32_e32 v10, v7
	s_nop 0
	v_mul_f32_e32 v7, v19, v10
	v_lshlrev_b32_e32 v20, 16, v8
	v_and_b32_e32 v8, 0xffff0000, v8
	v_mul_f32_e32 v10, 0xbfb8aa3b, v20
	v_mul_f32_e32 v11, 0xbfb8aa3b, v8
	v_exp_f32_e32 v10, v10
	v_exp_f32_e32 v11, v11
	v_rcp_f32_e32 v12, v6
	s_nop 0
	v_mul_f32_e32 v6, v18, v12
	v_pk_mul_f32 v[6:7], v[6:7], v[2:3]
	v_pk_add_f32 v[10:11], v[10:11], 1.0 op_sel_hi:[1,0]
	v_lshlrev_b32_e32 v2, 16, v4
	v_and_b32_e32 v3, 0xffff0000, v4
	v_and_b32_e32 v21, 0xffff0000, v9
	v_rcp_f32_e32 v4, v11
	s_nop 0
	v_mul_f32_e32 v11, v8, v4
	v_lshlrev_b32_e32 v12, 16, v9
	v_mul_f32_e32 v8, 0xbfb8aa3b, v12
	v_mul_f32_e32 v9, 0xbfb8aa3b, v21
	v_exp_f32_e32 v8, v8
	v_exp_f32_e32 v9, v9
	v_rcp_f32_e32 v4, v10
	s_nop 0
	v_mul_f32_e32 v10, v20, v4
	v_pk_mul_f32 v[18:19], v[10:11], v[2:3]
	v_pk_add_f32 v[8:9], v[8:9], 1.0 op_sel_hi:[1,0]
	v_lshlrev_b32_e32 v2, 16, v5
	v_and_b32_e32 v3, 0xffff0000, v5
	v_rcp_f32_e32 v4, v9
	s_nop 0
	v_mul_f32_e32 v5, v21, v4
	v_rcp_f32_e32 v4, v8
	s_nop 0
	v_mul_f32_e32 v4, v12, v4
	ds_read_b128 v[10:13], v164 offset:288
	v_pk_mul_f32 v[20:21], v[4:5], v[2:3]
	v_cvt_pk_bf16_f32 v2, v16, v17
	v_cvt_pk_bf16_f32 v4, v18, v19
	ds_read_b128 v[16:19], v164 offset:416
	s_waitcnt lgkmcnt(1)
	v_lshlrev_b32_e32 v24, 16, v10
	v_and_b32_e32 v10, 0xffff0000, v10
	v_mul_f32_e32 v5, 0xbfb8aa3b, v24
	v_exp_f32_e32 v22, v5
	v_mul_f32_e32 v5, 0xbfb8aa3b, v10
	v_exp_f32_e32 v23, v5
	v_cvt_pk_bf16_f32 v5, v20, v21
	v_cvt_pk_bf16_f32 v3, v6, v7
	ds_read_b128 v[6:9], v164 offset:304
	v_pk_add_f32 v[20:21], v[22:23], 1.0 op_sel_hi:[1,0]
	s_waitcnt lgkmcnt(1)
	v_lshlrev_b32_e32 v22, 16, v16
	v_and_b32_e32 v23, 0xffff0000, v16
	global_store_dwordx4 v[14:15], v[2:5], off offset:16
	ds_read_b128 v[2:5], v164 offset:432
	v_rcp_f32_e32 v16, v21
	s_nop 0
	v_mul_f32_e32 v21, v10, v16
	v_and_b32_e32 v27, 0xffff0000, v11
	v_lshlrev_b32_e32 v26, 16, v11
	v_mul_f32_e32 v10, 0xbfb8aa3b, v26
	v_mul_f32_e32 v11, 0xbfb8aa3b, v27
	v_exp_f32_e32 v10, v10
	v_exp_f32_e32 v11, v11
	v_rcp_f32_e32 v16, v20
	s_nop 0
	v_mul_f32_e32 v20, v24, v16
	v_pk_mul_f32 v[20:21], v[20:21], v[22:23]
	v_pk_add_f32 v[10:11], v[10:11], 1.0 op_sel_hi:[1,0]
	v_lshlrev_b32_e32 v16, 16, v17
	v_and_b32_e32 v17, 0xffff0000, v17
	v_rcp_f32_e32 v22, v11
	s_nop 0
	v_mul_f32_e32 v11, v27, v22
	v_lshlrev_b32_e32 v27, 16, v12
	v_and_b32_e32 v12, 0xffff0000, v12
	v_mul_f32_e32 v22, 0xbfb8aa3b, v27
	v_mul_f32_e32 v23, 0xbfb8aa3b, v12
	v_exp_f32_e32 v22, v22
	v_exp_f32_e32 v23, v23
	v_rcp_f32_e32 v24, v10
	s_nop 0
	v_mul_f32_e32 v10, v26, v24
	v_pk_mul_f32 v[16:17], v[10:11], v[16:17]
	v_pk_add_f32 v[22:23], v[22:23], 1.0 op_sel_hi:[1,0]
	v_lshlrev_b32_e32 v10, 16, v18
	v_and_b32_e32 v11, 0xffff0000, v18
	v_rcp_f32_e32 v18, v23
	s_nop 0
	v_mul_f32_e32 v23, v12, v18
	v_and_b32_e32 v26, 0xffff0000, v13
	v_lshlrev_b32_e32 v25, 16, v13
	v_mul_f32_e32 v12, 0xbfb8aa3b, v25
	v_mul_f32_e32 v13, 0xbfb8aa3b, v26
	v_exp_f32_e32 v12, v12
	v_exp_f32_e32 v13, v13
	v_rcp_f32_e32 v18, v22
	s_nop 0
	v_mul_f32_e32 v22, v27, v18
	v_pk_mul_f32 v[22:23], v[22:23], v[10:11]
	v_pk_add_f32 v[12:13], v[12:13], 1.0 op_sel_hi:[1,0]
	v_lshlrev_b32_e32 v10, 16, v19
	v_and_b32_e32 v11, 0xffff0000, v19
	v_rcp_f32_e32 v18, v13
	s_nop 0
	v_mul_f32_e32 v13, v26, v18
	v_rcp_f32_e32 v18, v12
	s_nop 0
	v_mul_f32_e32 v12, v25, v18
	s_waitcnt lgkmcnt(1)
	v_lshlrev_b32_e32 v24, 16, v6
	v_pk_mul_f32 v[18:19], v[12:13], v[10:11]
	v_and_b32_e32 v6, 0xffff0000, v6
	v_mul_f32_e32 v11, 0xbfb8aa3b, v24
	v_cvt_pk_bf16_f32 v10, v20, v21
	v_exp_f32_e32 v20, v11
	v_mul_f32_e32 v11, 0xbfb8aa3b, v6
	v_exp_f32_e32 v21, v11
	v_cvt_pk_bf16_f32 v11, v16, v17
	v_cvt_pk_bf16_f32 v13, v18, v19
	v_cvt_pk_bf16_f32 v12, v22, v23
	v_pk_add_f32 v[16:17], v[20:21], 1.0 op_sel_hi:[1,0]
	global_store_dwordx4 v[14:15], v[10:13], off offset:32
	s_nop 1
	s_waitcnt lgkmcnt(0)
	v_lshlrev_b32_e32 v10, 16, v2
	v_and_b32_e32 v11, 0xffff0000, v2
	v_rcp_f32_e32 v2, v17
	s_nop 0
	v_mul_f32_e32 v13, v6, v2
	v_lshlrev_b32_e32 v17, 16, v7
	v_and_b32_e32 v18, 0xffff0000, v7
	v_mul_f32_e32 v6, 0xbfb8aa3b, v17
	v_mul_f32_e32 v7, 0xbfb8aa3b, v18
	v_exp_f32_e32 v6, v6
	v_exp_f32_e32 v7, v7
	v_rcp_f32_e32 v2, v16
	s_nop 0
	v_mul_f32_e32 v12, v24, v2
	v_pk_mul_f32 v[10:11], v[12:13], v[10:11]
	v_pk_add_f32 v[6:7], v[6:7], 1.0 op_sel_hi:[1,0]
	v_lshlrev_b32_e32 v2, 16, v3
	v_and_b32_e32 v3, 0xffff0000, v3
	v_rcp_f32_e32 v12, v7
	s_nop 0
	v_mul_f32_e32 v7, v18, v12
	v_lshlrev_b32_e32 v19, 16, v8
	v_and_b32_e32 v8, 0xffff0000, v8
	v_mul_f32_e32 v12, 0xbfb8aa3b, v19
	v_mul_f32_e32 v13, 0xbfb8aa3b, v8
	v_exp_f32_e32 v12, v12
	v_exp_f32_e32 v13, v13
	v_rcp_f32_e32 v16, v6
	s_nop 0
	v_mul_f32_e32 v6, v17, v16
	v_pk_mul_f32 v[6:7], v[6:7], v[2:3]
	v_pk_add_f32 v[12:13], v[12:13], 1.0 op_sel_hi:[1,0]
	v_lshlrev_b32_e32 v2, 16, v4
	v_and_b32_e32 v3, 0xffff0000, v4
	v_rcp_f32_e32 v4, v13
	s_nop 0
	v_mul_f32_e32 v13, v8, v4
	v_and_b32_e32 v18, 0xffff0000, v9
	v_lshlrev_b32_e32 v16, 16, v9
	v_mul_f32_e32 v8, 0xbfb8aa3b, v16
	v_mul_f32_e32 v9, 0xbfb8aa3b, v18
	v_exp_f32_e32 v8, v8
	v_exp_f32_e32 v9, v9
	v_rcp_f32_e32 v4, v12
	s_nop 0
	v_mul_f32_e32 v12, v19, v4
	v_pk_mul_f32 v[12:13], v[12:13], v[2:3]
	v_pk_add_f32 v[8:9], v[8:9], 1.0 op_sel_hi:[1,0]
	v_lshlrev_b32_e32 v2, 16, v5
	v_and_b32_e32 v3, 0xffff0000, v5
	v_rcp_f32_e32 v4, v9
	s_nop 0
	v_mul_f32_e32 v5, v18, v4
	v_rcp_f32_e32 v4, v8
	s_nop 0
	v_mul_f32_e32 v4, v16, v4
	v_pk_mul_f32 v[8:9], v[4:5], v[2:3]
	v_cvt_pk_bf16_f32 v2, v10, v11
	v_cvt_pk_bf16_f32 v3, v6, v7
	v_cvt_pk_bf16_f32 v4, v12, v13
	v_cvt_pk_bf16_f32 v5, v8, v9
	global_store_dwordx4 v[14:15], v[2:5], off offset:48
	s_branch .LBB0_289
